# plus GLU GEMM epilogue rewritten: gate/bias loads of a 128-row half issued together (second half into freed accumulators), counted vmcnt waits
# baseline (speedup 1.0000x reference)
.LBB0_381:
	v_lshl_or_b32 v128, s33, 8, v162
	v_ashrrev_i32_e32 v129, 31, v128
	v_lshl_add_u64 v[152:153], v[128:129], 2, s[22:23]
	global_load_dwordx4 v[166:169], v[152:153], off
	global_load_dwordx4 v[170:173], v[152:153], off offset:16
	global_load_dwordx4 v[174:177], v[152:153], off offset:512
	global_load_dwordx4 v[178:181], v[152:153], off offset:528
	v_lshlrev_b64 v[154:155], 1, v[128:129]
	v_lshl_add_u32 v156, s36, 8, v160
	v_ashrrev_i32_e32 v157, 31, v156
	s_andn2_b64 vcc, exec, s[0:1]
	s_mov_b64 s[0:1], -1
	v_mov_b64_e32 v[158:159], s[12:13]
	v_mad_i64_i32 v[130:131], s[38:39], v156, s70, v[158:159]
	v_lshl_add_u64 v[130:131], v[130:131], 0, v[154:155]
	v_lshlrev_b64 v[132:133], 11, v[156:157]
	v_lshl_add_u64 v[132:133], s[6:7], 0, v[132:133]
	v_lshl_add_u64 v[132:133], v[132:133], 0, v[154:155]
	v_lshlrev_b64 v[134:135], 12, v[156:157]
	v_lshl_add_u64 v[134:135], s[14:15], 0, v[134:135]
	v_lshl_add_u64 v[134:135], v[134:135], 0, v[154:155]
	s_mov_b32 s38, 0x0
	s_mov_b32 s39, 0
	v_lshl_add_u64 v[128:129], v[130:131], 0, s[38:39]
	global_load_dwordx4 v[214:217], v[128:129], off
	global_load_dwordx4 v[218:221], v[128:129], off offset:256
	s_mov_b32 s38, 0x0
	v_lshl_add_u64 v[128:129], v[132:133], 0, s[38:39]
	global_load_dwordx4 v[182:185], v[128:129], off
	global_load_dwordx4 v[186:189], v[128:129], off offset:256
	s_mov_b32 s38, 0x30000
	s_mov_b32 s39, 0
	v_lshl_add_u64 v[128:129], v[130:131], 0, s[38:39]
	global_load_dwordx4 v[222:225], v[128:129], off
	global_load_dwordx4 v[226:229], v[128:129], off offset:256
	s_mov_b32 s38, 0x8000
	v_lshl_add_u64 v[128:129], v[132:133], 0, s[38:39]
	global_load_dwordx4 v[190:193], v[128:129], off
	global_load_dwordx4 v[194:197], v[128:129], off offset:256
	s_mov_b32 s38, 0x60000
	s_mov_b32 s39, 0
	v_lshl_add_u64 v[128:129], v[130:131], 0, s[38:39]
	global_load_dwordx4 v[230:233], v[128:129], off
	global_load_dwordx4 v[234:237], v[128:129], off offset:256
	s_mov_b32 s38, 0x10000
	v_lshl_add_u64 v[128:129], v[132:133], 0, s[38:39]
	global_load_dwordx4 v[198:201], v[128:129], off
	global_load_dwordx4 v[202:205], v[128:129], off offset:256
	s_mov_b32 s38, 0x90000
	s_mov_b32 s39, 0
	v_lshl_add_u64 v[128:129], v[130:131], 0, s[38:39]
	global_load_dwordx4 v[238:241], v[128:129], off
	global_load_dwordx4 v[242:245], v[128:129], off offset:256
	s_mov_b32 s38, 0x18000
	v_lshl_add_u64 v[128:129], v[132:133], 0, s[38:39]
	global_load_dwordx4 v[206:209], v[128:129], off
	global_load_dwordx4 v[210:213], v[128:129], off offset:256
	s_waitcnt vmcnt(16)
	s_waitcnt vmcnt(12)
	v_add_f32_e32 v124, v124, v166
	v_add_f32_e32 v125, v125, v167
	v_add_f32_e32 v126, v126, v168
	v_add_f32_e32 v127, v127, v169
	v_mul_f32_e32 v124, 0xbfb8aa3b, v124
	v_mul_f32_e32 v125, 0xbfb8aa3b, v125
	v_mul_f32_e32 v126, 0xbfb8aa3b, v126
	v_mul_f32_e32 v127, 0xbfb8aa3b, v127
	v_exp_f32_e32 v124, v124
	v_exp_f32_e32 v125, v125
	v_exp_f32_e32 v126, v126
	v_exp_f32_e32 v127, v127
	v_add_f32_e32 v124, 1.0, v124
	v_add_f32_e32 v125, 1.0, v125
	v_add_f32_e32 v126, 1.0, v126
	v_add_f32_e32 v127, 1.0, v127
	v_rcp_f32_e32 v124, v124
	v_rcp_f32_e32 v125, v125
	v_rcp_f32_e32 v126, v126
	v_rcp_f32_e32 v127, v127
	v_lshlrev_b32_e32 v156, 16, v182
	v_and_b32_e32 v157, 0xffff0000, v182
	v_lshlrev_b32_e32 v158, 16, v183
	v_and_b32_e32 v159, 0xffff0000, v183
	v_mul_f32_e32 v124, v124, v156
	v_mul_f32_e32 v125, v125, v157
	v_mul_f32_e32 v126, v126, v158
	v_mul_f32_e32 v127, v127, v159
	v_lshlrev_b32_e32 v156, 16, v214
	v_and_b32_e32 v157, 0xffff0000, v214
	v_lshlrev_b32_e32 v158, 16, v215
	v_and_b32_e32 v159, 0xffff0000, v215
	v_mul_f32_e32 v124, v124, v156
	v_mul_f32_e32 v125, v125, v157
	v_mul_f32_e32 v126, v126, v158
	v_mul_f32_e32 v127, v127, v159
	v_mul_f32_e32 v156, 0xbfb8aa3b, v156
	v_mul_f32_e32 v157, 0xbfb8aa3b, v157
	v_mul_f32_e32 v158, 0xbfb8aa3b, v158
	v_mul_f32_e32 v159, 0xbfb8aa3b, v159
	v_exp_f32_e32 v156, v156
	v_exp_f32_e32 v157, v157
	v_exp_f32_e32 v158, v158
	v_exp_f32_e32 v159, v159
	v_add_f32_e32 v156, 1.0, v156
	v_add_f32_e32 v157, 1.0, v157
	v_add_f32_e32 v158, 1.0, v158
	v_add_f32_e32 v159, 1.0, v159
	v_rcp_f32_e32 v156, v156
	v_rcp_f32_e32 v157, v157
	v_rcp_f32_e32 v158, v158
	v_rcp_f32_e32 v159, v159
	v_mul_f32_e32 v124, v156, v124
	v_mul_f32_e32 v125, v157, v125
	v_mul_f32_e32 v126, v158, v126
	v_mul_f32_e32 v127, v159, v127
	v_cvt_pk_bf16_f32 v246, v124, v125
	v_cvt_pk_bf16_f32 v247, v126, v127
	v_add_f32_e32 v120, v120, v170
	v_add_f32_e32 v121, v121, v171
	v_add_f32_e32 v122, v122, v172
	v_add_f32_e32 v123, v123, v173
	v_mul_f32_e32 v120, 0xbfb8aa3b, v120
	v_mul_f32_e32 v121, 0xbfb8aa3b, v121
	v_mul_f32_e32 v122, 0xbfb8aa3b, v122
	v_mul_f32_e32 v123, 0xbfb8aa3b, v123
	v_exp_f32_e32 v120, v120
	v_exp_f32_e32 v121, v121
	v_exp_f32_e32 v122, v122
	v_exp_f32_e32 v123, v123
	v_add_f32_e32 v120, 1.0, v120
	v_add_f32_e32 v121, 1.0, v121
	v_add_f32_e32 v122, 1.0, v122
	v_add_f32_e32 v123, 1.0, v123
	v_rcp_f32_e32 v120, v120
	v_rcp_f32_e32 v121, v121
	v_rcp_f32_e32 v122, v122
	v_rcp_f32_e32 v123, v123
	v_lshlrev_b32_e32 v156, 16, v184
	v_and_b32_e32 v157, 0xffff0000, v184
	v_lshlrev_b32_e32 v158, 16, v185
	v_and_b32_e32 v159, 0xffff0000, v185
	v_mul_f32_e32 v120, v120, v156
	v_mul_f32_e32 v121, v121, v157
	v_mul_f32_e32 v122, v122, v158
	v_mul_f32_e32 v123, v123, v159
	v_lshlrev_b32_e32 v156, 16, v216
	v_and_b32_e32 v157, 0xffff0000, v216
	v_lshlrev_b32_e32 v158, 16, v217
	v_and_b32_e32 v159, 0xffff0000, v217
	v_mul_f32_e32 v120, v120, v156
	v_mul_f32_e32 v121, v121, v157
	v_mul_f32_e32 v122, v122, v158
	v_mul_f32_e32 v123, v123, v159
	v_mul_f32_e32 v156, 0xbfb8aa3b, v156
	v_mul_f32_e32 v157, 0xbfb8aa3b, v157
	v_mul_f32_e32 v158, 0xbfb8aa3b, v158
	v_mul_f32_e32 v159, 0xbfb8aa3b, v159
	v_exp_f32_e32 v156, v156
	v_exp_f32_e32 v157, v157
	v_exp_f32_e32 v158, v158
	v_exp_f32_e32 v159, v159
	v_add_f32_e32 v156, 1.0, v156
	v_add_f32_e32 v157, 1.0, v157
	v_add_f32_e32 v158, 1.0, v158
	v_add_f32_e32 v159, 1.0, v159
	v_rcp_f32_e32 v156, v156
	v_rcp_f32_e32 v157, v157
	v_rcp_f32_e32 v158, v158
	v_rcp_f32_e32 v159, v159
	v_mul_f32_e32 v120, v156, v120
	v_mul_f32_e32 v121, v157, v121
	v_mul_f32_e32 v122, v158, v122
	v_mul_f32_e32 v123, v159, v123
	v_cvt_pk_bf16_f32 v248, v120, v121
	v_cvt_pk_bf16_f32 v249, v122, v123
	s_mov_b32 s38, 0x0
	s_mov_b32 s39, 0
	v_lshl_add_u64 v[128:129], v[134:135], 0, s[38:39]
	global_store_dwordx4 v[128:129], v[246:249], off
	v_add_f32_e32 v116, v116, v174
	v_add_f32_e32 v117, v117, v175
	v_add_f32_e32 v118, v118, v176
	v_add_f32_e32 v119, v119, v177
	v_mul_f32_e32 v116, 0xbfb8aa3b, v116
	v_mul_f32_e32 v117, 0xbfb8aa3b, v117
	v_mul_f32_e32 v118, 0xbfb8aa3b, v118
	v_mul_f32_e32 v119, 0xbfb8aa3b, v119
	v_exp_f32_e32 v116, v116
	v_exp_f32_e32 v117, v117
	v_exp_f32_e32 v118, v118
	v_exp_f32_e32 v119, v119
	v_add_f32_e32 v116, 1.0, v116
	v_add_f32_e32 v117, 1.0, v117
	v_add_f32_e32 v118, 1.0, v118
	v_add_f32_e32 v119, 1.0, v119
	v_rcp_f32_e32 v116, v116
	v_rcp_f32_e32 v117, v117
	v_rcp_f32_e32 v118, v118
	v_rcp_f32_e32 v119, v119
	v_lshlrev_b32_e32 v156, 16, v186
	v_and_b32_e32 v157, 0xffff0000, v186
	v_lshlrev_b32_e32 v158, 16, v187
	v_and_b32_e32 v159, 0xffff0000, v187
	v_mul_f32_e32 v116, v116, v156
	v_mul_f32_e32 v117, v117, v157
	v_mul_f32_e32 v118, v118, v158
	v_mul_f32_e32 v119, v119, v159
	v_lshlrev_b32_e32 v156, 16, v218
	v_and_b32_e32 v157, 0xffff0000, v218
	v_lshlrev_b32_e32 v158, 16, v219
	v_and_b32_e32 v159, 0xffff0000, v219
	v_mul_f32_e32 v116, v116, v156
	v_mul_f32_e32 v117, v117, v157
	v_mul_f32_e32 v118, v118, v158
	v_mul_f32_e32 v119, v119, v159
	v_mul_f32_e32 v156, 0xbfb8aa3b, v156
	v_mul_f32_e32 v157, 0xbfb8aa3b, v157
	v_mul_f32_e32 v158, 0xbfb8aa3b, v158
	v_mul_f32_e32 v159, 0xbfb8aa3b, v159
	v_exp_f32_e32 v156, v156
	v_exp_f32_e32 v157, v157
	v_exp_f32_e32 v158, v158
	v_exp_f32_e32 v159, v159
	v_add_f32_e32 v156, 1.0, v156
	v_add_f32_e32 v157, 1.0, v157
	v_add_f32_e32 v158, 1.0, v158
	v_add_f32_e32 v159, 1.0, v159
	v_rcp_f32_e32 v156, v156
	v_rcp_f32_e32 v157, v157
	v_rcp_f32_e32 v158, v158
	v_rcp_f32_e32 v159, v159
	v_mul_f32_e32 v116, v156, v116
	v_mul_f32_e32 v117, v157, v117
	v_mul_f32_e32 v118, v158, v118
	v_mul_f32_e32 v119, v159, v119
	v_cvt_pk_bf16_f32 v250, v116, v117
	v_cvt_pk_bf16_f32 v251, v118, v119
	v_add_f32_e32 v112, v112, v178
	v_add_f32_e32 v113, v113, v179
	v_add_f32_e32 v114, v114, v180
	v_add_f32_e32 v115, v115, v181
	v_mul_f32_e32 v112, 0xbfb8aa3b, v112
	v_mul_f32_e32 v113, 0xbfb8aa3b, v113
	v_mul_f32_e32 v114, 0xbfb8aa3b, v114
	v_mul_f32_e32 v115, 0xbfb8aa3b, v115
	v_exp_f32_e32 v112, v112
	v_exp_f32_e32 v113, v113
	v_exp_f32_e32 v114, v114
	v_exp_f32_e32 v115, v115
	v_add_f32_e32 v112, 1.0, v112
	v_add_f32_e32 v113, 1.0, v113
	v_add_f32_e32 v114, 1.0, v114
	v_add_f32_e32 v115, 1.0, v115
	v_rcp_f32_e32 v112, v112
	v_rcp_f32_e32 v113, v113
	v_rcp_f32_e32 v114, v114
	v_rcp_f32_e32 v115, v115
	v_lshlrev_b32_e32 v156, 16, v188
	v_and_b32_e32 v157, 0xffff0000, v188
	v_lshlrev_b32_e32 v158, 16, v189
	v_and_b32_e32 v159, 0xffff0000, v189
	v_mul_f32_e32 v112, v112, v156
	v_mul_f32_e32 v113, v113, v157
	v_mul_f32_e32 v114, v114, v158
	v_mul_f32_e32 v115, v115, v159
	v_lshlrev_b32_e32 v156, 16, v220
	v_and_b32_e32 v157, 0xffff0000, v220
	v_lshlrev_b32_e32 v158, 16, v221
	v_and_b32_e32 v159, 0xffff0000, v221
	v_mul_f32_e32 v112, v112, v156
	v_mul_f32_e32 v113, v113, v157
	v_mul_f32_e32 v114, v114, v158
	v_mul_f32_e32 v115, v115, v159
	v_mul_f32_e32 v156, 0xbfb8aa3b, v156
	v_mul_f32_e32 v157, 0xbfb8aa3b, v157
	v_mul_f32_e32 v158, 0xbfb8aa3b, v158
	v_mul_f32_e32 v159, 0xbfb8aa3b, v159
	v_exp_f32_e32 v156, v156
	v_exp_f32_e32 v157, v157
	v_exp_f32_e32 v158, v158
	v_exp_f32_e32 v159, v159
	v_add_f32_e32 v156, 1.0, v156
	v_add_f32_e32 v157, 1.0, v157
	v_add_f32_e32 v158, 1.0, v158
	v_add_f32_e32 v159, 1.0, v159
	v_rcp_f32_e32 v156, v156
	v_rcp_f32_e32 v157, v157
	v_rcp_f32_e32 v158, v158
	v_rcp_f32_e32 v159, v159
	v_mul_f32_e32 v112, v156, v112
	v_mul_f32_e32 v113, v157, v113
	v_mul_f32_e32 v114, v158, v114
	v_mul_f32_e32 v115, v159, v115
	v_cvt_pk_bf16_f32 v252, v112, v113
	v_cvt_pk_bf16_f32 v253, v114, v115
	global_store_dwordx4 v[128:129], v[250:253], off offset:256
	s_mov_b32 s38, 0x180000
	s_mov_b32 s39, 0
	v_lshl_add_u64 v[128:129], v[130:131], 0, s[38:39]
	global_load_dwordx4 v[116:119], v[128:129], off
	global_load_dwordx4 v[112:115], v[128:129], off offset:256
	s_mov_b32 s38, 0x40000
	v_lshl_add_u64 v[128:129], v[132:133], 0, s[38:39]
	global_load_dwordx4 v[124:127], v[128:129], off
	global_load_dwordx4 v[120:123], v[128:129], off offset:256
	s_waitcnt vmcnt(14)
	v_add_f32_e32 v108, v108, v166
	v_add_f32_e32 v109, v109, v167
	v_add_f32_e32 v110, v110, v168
	v_add_f32_e32 v111, v111, v169
	v_mul_f32_e32 v108, 0xbfb8aa3b, v108
	v_mul_f32_e32 v109, 0xbfb8aa3b, v109
	v_mul_f32_e32 v110, 0xbfb8aa3b, v110
	v_mul_f32_e32 v111, 0xbfb8aa3b, v111
	v_exp_f32_e32 v108, v108
	v_exp_f32_e32 v109, v109
	v_exp_f32_e32 v110, v110
	v_exp_f32_e32 v111, v111
	v_add_f32_e32 v108, 1.0, v108
	v_add_f32_e32 v109, 1.0, v109
	v_add_f32_e32 v110, 1.0, v110
	v_add_f32_e32 v111, 1.0, v111
	v_rcp_f32_e32 v108, v108
	v_rcp_f32_e32 v109, v109
	v_rcp_f32_e32 v110, v110
	v_rcp_f32_e32 v111, v111
	v_lshlrev_b32_e32 v156, 16, v190
	v_and_b32_e32 v157, 0xffff0000, v190
	v_lshlrev_b32_e32 v158, 16, v191
	v_and_b32_e32 v159, 0xffff0000, v191
	v_mul_f32_e32 v108, v108, v156
	v_mul_f32_e32 v109, v109, v157
	v_mul_f32_e32 v110, v110, v158
	v_mul_f32_e32 v111, v111, v159
	v_lshlrev_b32_e32 v156, 16, v222
	v_and_b32_e32 v157, 0xffff0000, v222
	v_lshlrev_b32_e32 v158, 16, v223
	v_and_b32_e32 v159, 0xffff0000, v223
	v_mul_f32_e32 v108, v108, v156
	v_mul_f32_e32 v109, v109, v157
	v_mul_f32_e32 v110, v110, v158
	v_mul_f32_e32 v111, v111, v159
	v_mul_f32_e32 v156, 0xbfb8aa3b, v156
	v_mul_f32_e32 v157, 0xbfb8aa3b, v157
	v_mul_f32_e32 v158, 0xbfb8aa3b, v158
	v_mul_f32_e32 v159, 0xbfb8aa3b, v159
	v_exp_f32_e32 v156, v156
	v_exp_f32_e32 v157, v157
	v_exp_f32_e32 v158, v158
	v_exp_f32_e32 v159, v159
	v_add_f32_e32 v156, 1.0, v156
	v_add_f32_e32 v157, 1.0, v157
	v_add_f32_e32 v158, 1.0, v158
	v_add_f32_e32 v159, 1.0, v159
	v_rcp_f32_e32 v156, v156
	v_rcp_f32_e32 v157, v157
	v_rcp_f32_e32 v158, v158
	v_rcp_f32_e32 v159, v159
	v_mul_f32_e32 v108, v156, v108
	v_mul_f32_e32 v109, v157, v109
	v_mul_f32_e32 v110, v158, v110
	v_mul_f32_e32 v111, v159, v111
	v_cvt_pk_bf16_f32 v246, v108, v109
	v_cvt_pk_bf16_f32 v247, v110, v111
	v_add_f32_e32 v104, v104, v170
	v_add_f32_e32 v105, v105, v171
	v_add_f32_e32 v106, v106, v172
	v_add_f32_e32 v107, v107, v173
	v_mul_f32_e32 v104, 0xbfb8aa3b, v104
	v_mul_f32_e32 v105, 0xbfb8aa3b, v105
	v_mul_f32_e32 v106, 0xbfb8aa3b, v106
	v_mul_f32_e32 v107, 0xbfb8aa3b, v107
	v_exp_f32_e32 v104, v104
	v_exp_f32_e32 v105, v105
	v_exp_f32_e32 v106, v106
	v_exp_f32_e32 v107, v107
	v_add_f32_e32 v104, 1.0, v104
	v_add_f32_e32 v105, 1.0, v105
	v_add_f32_e32 v106, 1.0, v106
	v_add_f32_e32 v107, 1.0, v107
	v_rcp_f32_e32 v104, v104
	v_rcp_f32_e32 v105, v105
	v_rcp_f32_e32 v106, v106
	v_rcp_f32_e32 v107, v107
	v_lshlrev_b32_e32 v156, 16, v192
	v_and_b32_e32 v157, 0xffff0000, v192
	v_lshlrev_b32_e32 v158, 16, v193
	v_and_b32_e32 v159, 0xffff0000, v193
	v_mul_f32_e32 v104, v104, v156
	v_mul_f32_e32 v105, v105, v157
	v_mul_f32_e32 v106, v106, v158
	v_mul_f32_e32 v107, v107, v159
	v_lshlrev_b32_e32 v156, 16, v224
	v_and_b32_e32 v157, 0xffff0000, v224
	v_lshlrev_b32_e32 v158, 16, v225
	v_and_b32_e32 v159, 0xffff0000, v225
	v_mul_f32_e32 v104, v104, v156
	v_mul_f32_e32 v105, v105, v157
	v_mul_f32_e32 v106, v106, v158
	v_mul_f32_e32 v107, v107, v159
	v_mul_f32_e32 v156, 0xbfb8aa3b, v156
	v_mul_f32_e32 v157, 0xbfb8aa3b, v157
	v_mul_f32_e32 v158, 0xbfb8aa3b, v158
	v_mul_f32_e32 v159, 0xbfb8aa3b, v159
	v_exp_f32_e32 v156, v156
	v_exp_f32_e32 v157, v157
	v_exp_f32_e32 v158, v158
	v_exp_f32_e32 v159, v159
	v_add_f32_e32 v156, 1.0, v156
	v_add_f32_e32 v157, 1.0, v157
	v_add_f32_e32 v158, 1.0, v158
	v_add_f32_e32 v159, 1.0, v159
	v_rcp_f32_e32 v156, v156
	v_rcp_f32_e32 v157, v157
	v_rcp_f32_e32 v158, v158
	v_rcp_f32_e32 v159, v159
	v_mul_f32_e32 v104, v156, v104
	v_mul_f32_e32 v105, v157, v105
	v_mul_f32_e32 v106, v158, v106
	v_mul_f32_e32 v107, v159, v107
	v_cvt_pk_bf16_f32 v248, v104, v105
	v_cvt_pk_bf16_f32 v249, v106, v107
	s_mov_b32 s38, 0x10000
	s_mov_b32 s39, 0
	v_lshl_add_u64 v[128:129], v[134:135], 0, s[38:39]
	global_store_dwordx4 v[128:129], v[246:249], off
	v_add_f32_e32 v100, v100, v174
	v_add_f32_e32 v101, v101, v175
	v_add_f32_e32 v102, v102, v176
	v_add_f32_e32 v103, v103, v177
	v_mul_f32_e32 v100, 0xbfb8aa3b, v100
	v_mul_f32_e32 v101, 0xbfb8aa3b, v101
	v_mul_f32_e32 v102, 0xbfb8aa3b, v102
	v_mul_f32_e32 v103, 0xbfb8aa3b, v103
	v_exp_f32_e32 v100, v100
	v_exp_f32_e32 v101, v101
	v_exp_f32_e32 v102, v102
	v_exp_f32_e32 v103, v103
	v_add_f32_e32 v100, 1.0, v100
	v_add_f32_e32 v101, 1.0, v101
	v_add_f32_e32 v102, 1.0, v102
	v_add_f32_e32 v103, 1.0, v103
	v_rcp_f32_e32 v100, v100
	v_rcp_f32_e32 v101, v101
	v_rcp_f32_e32 v102, v102
	v_rcp_f32_e32 v103, v103
	v_lshlrev_b32_e32 v156, 16, v194
	v_and_b32_e32 v157, 0xffff0000, v194
	v_lshlrev_b32_e32 v158, 16, v195
	v_and_b32_e32 v159, 0xffff0000, v195
	v_mul_f32_e32 v100, v100, v156
	v_mul_f32_e32 v101, v101, v157
	v_mul_f32_e32 v102, v102, v158
	v_mul_f32_e32 v103, v103, v159
	v_lshlrev_b32_e32 v156, 16, v226
	v_and_b32_e32 v157, 0xffff0000, v226
	v_lshlrev_b32_e32 v158, 16, v227
	v_and_b32_e32 v159, 0xffff0000, v227
	v_mul_f32_e32 v100, v100, v156
	v_mul_f32_e32 v101, v101, v157
	v_mul_f32_e32 v102, v102, v158
	v_mul_f32_e32 v103, v103, v159
	v_mul_f32_e32 v156, 0xbfb8aa3b, v156
	v_mul_f32_e32 v157, 0xbfb8aa3b, v157
	v_mul_f32_e32 v158, 0xbfb8aa3b, v158
	v_mul_f32_e32 v159, 0xbfb8aa3b, v159
	v_exp_f32_e32 v156, v156
	v_exp_f32_e32 v157, v157
	v_exp_f32_e32 v158, v158
	v_exp_f32_e32 v159, v159
	v_add_f32_e32 v156, 1.0, v156
	v_add_f32_e32 v157, 1.0, v157
	v_add_f32_e32 v158, 1.0, v158
	v_add_f32_e32 v159, 1.0, v159
	v_rcp_f32_e32 v156, v156
	v_rcp_f32_e32 v157, v157
	v_rcp_f32_e32 v158, v158
	v_rcp_f32_e32 v159, v159
	v_mul_f32_e32 v100, v156, v100
	v_mul_f32_e32 v101, v157, v101
	v_mul_f32_e32 v102, v158, v102
	v_mul_f32_e32 v103, v159, v103
	v_cvt_pk_bf16_f32 v250, v100, v101
	v_cvt_pk_bf16_f32 v251, v102, v103
	v_add_f32_e32 v96, v96, v178
	v_add_f32_e32 v97, v97, v179
	v_add_f32_e32 v98, v98, v180
	v_add_f32_e32 v99, v99, v181
	v_mul_f32_e32 v96, 0xbfb8aa3b, v96
	v_mul_f32_e32 v97, 0xbfb8aa3b, v97
	v_mul_f32_e32 v98, 0xbfb8aa3b, v98
	v_mul_f32_e32 v99, 0xbfb8aa3b, v99
	v_exp_f32_e32 v96, v96
	v_exp_f32_e32 v97, v97
	v_exp_f32_e32 v98, v98
	v_exp_f32_e32 v99, v99
	v_add_f32_e32 v96, 1.0, v96
	v_add_f32_e32 v97, 1.0, v97
	v_add_f32_e32 v98, 1.0, v98
	v_add_f32_e32 v99, 1.0, v99
	v_rcp_f32_e32 v96, v96
	v_rcp_f32_e32 v97, v97
	v_rcp_f32_e32 v98, v98
	v_rcp_f32_e32 v99, v99
	v_lshlrev_b32_e32 v156, 16, v196
	v_and_b32_e32 v157, 0xffff0000, v196
	v_lshlrev_b32_e32 v158, 16, v197
	v_and_b32_e32 v159, 0xffff0000, v197
	v_mul_f32_e32 v96, v96, v156
	v_mul_f32_e32 v97, v97, v157
	v_mul_f32_e32 v98, v98, v158
	v_mul_f32_e32 v99, v99, v159
	v_lshlrev_b32_e32 v156, 16, v228
	v_and_b32_e32 v157, 0xffff0000, v228
	v_lshlrev_b32_e32 v158, 16, v229
	v_and_b32_e32 v159, 0xffff0000, v229
	v_mul_f32_e32 v96, v96, v156
	v_mul_f32_e32 v97, v97, v157
	v_mul_f32_e32 v98, v98, v158
	v_mul_f32_e32 v99, v99, v159
	v_mul_f32_e32 v156, 0xbfb8aa3b, v156
	v_mul_f32_e32 v157, 0xbfb8aa3b, v157
	v_mul_f32_e32 v158, 0xbfb8aa3b, v158
	v_mul_f32_e32 v159, 0xbfb8aa3b, v159
	v_exp_f32_e32 v156, v156
	v_exp_f32_e32 v157, v157
	v_exp_f32_e32 v158, v158
	v_exp_f32_e32 v159, v159
	v_add_f32_e32 v156, 1.0, v156
	v_add_f32_e32 v157, 1.0, v157
	v_add_f32_e32 v158, 1.0, v158
	v_add_f32_e32 v159, 1.0, v159
	v_rcp_f32_e32 v156, v156
	v_rcp_f32_e32 v157, v157
	v_rcp_f32_e32 v158, v158
	v_rcp_f32_e32 v159, v159
	v_mul_f32_e32 v96, v156, v96
	v_mul_f32_e32 v97, v157, v97
	v_mul_f32_e32 v98, v158, v98
	v_mul_f32_e32 v99, v159, v99
	v_cvt_pk_bf16_f32 v252, v96, v97
	v_cvt_pk_bf16_f32 v253, v98, v99
	global_store_dwordx4 v[128:129], v[250:253], off offset:256
	s_mov_b32 s38, 0x1b0000
	s_mov_b32 s39, 0
	v_lshl_add_u64 v[128:129], v[130:131], 0, s[38:39]
	global_load_dwordx4 v[100:103], v[128:129], off
	global_load_dwordx4 v[96:99], v[128:129], off offset:256
	s_mov_b32 s38, 0x48000
	v_lshl_add_u64 v[128:129], v[132:133], 0, s[38:39]
	global_load_dwordx4 v[108:111], v[128:129], off
	global_load_dwordx4 v[104:107], v[128:129], off offset:256
	s_waitcnt vmcnt(16)
	v_add_f32_e32 v92, v92, v166
	v_add_f32_e32 v93, v93, v167
	v_add_f32_e32 v94, v94, v168
	v_add_f32_e32 v95, v95, v169
	v_mul_f32_e32 v92, 0xbfb8aa3b, v92
	v_mul_f32_e32 v93, 0xbfb8aa3b, v93
	v_mul_f32_e32 v94, 0xbfb8aa3b, v94
	v_mul_f32_e32 v95, 0xbfb8aa3b, v95
	v_exp_f32_e32 v92, v92
	v_exp_f32_e32 v93, v93
	v_exp_f32_e32 v94, v94
	v_exp_f32_e32 v95, v95
	v_add_f32_e32 v92, 1.0, v92
	v_add_f32_e32 v93, 1.0, v93
	v_add_f32_e32 v94, 1.0, v94
	v_add_f32_e32 v95, 1.0, v95
	v_rcp_f32_e32 v92, v92
	v_rcp_f32_e32 v93, v93
	v_rcp_f32_e32 v94, v94
	v_rcp_f32_e32 v95, v95
	v_lshlrev_b32_e32 v156, 16, v198
	v_and_b32_e32 v157, 0xffff0000, v198
	v_lshlrev_b32_e32 v158, 16, v199
	v_and_b32_e32 v159, 0xffff0000, v199
	v_mul_f32_e32 v92, v92, v156
	v_mul_f32_e32 v93, v93, v157
	v_mul_f32_e32 v94, v94, v158
	v_mul_f32_e32 v95, v95, v159
	v_lshlrev_b32_e32 v156, 16, v230
	v_and_b32_e32 v157, 0xffff0000, v230
	v_lshlrev_b32_e32 v158, 16, v231
	v_and_b32_e32 v159, 0xffff0000, v231
	v_mul_f32_e32 v92, v92, v156
	v_mul_f32_e32 v93, v93, v157
	v_mul_f32_e32 v94, v94, v158
	v_mul_f32_e32 v95, v95, v159
	v_mul_f32_e32 v156, 0xbfb8aa3b, v156
	v_mul_f32_e32 v157, 0xbfb8aa3b, v157
	v_mul_f32_e32 v158, 0xbfb8aa3b, v158
	v_mul_f32_e32 v159, 0xbfb8aa3b, v159
	v_exp_f32_e32 v156, v156
	v_exp_f32_e32 v157, v157
	v_exp_f32_e32 v158, v158
	v_exp_f32_e32 v159, v159
	v_add_f32_e32 v156, 1.0, v156
	v_add_f32_e32 v157, 1.0, v157
	v_add_f32_e32 v158, 1.0, v158
	v_add_f32_e32 v159, 1.0, v159
	v_rcp_f32_e32 v156, v156
	v_rcp_f32_e32 v157, v157
	v_rcp_f32_e32 v158, v158
	v_rcp_f32_e32 v159, v159
	v_mul_f32_e32 v92, v156, v92
	v_mul_f32_e32 v93, v157, v93
	v_mul_f32_e32 v94, v158, v94
	v_mul_f32_e32 v95, v159, v95
	v_cvt_pk_bf16_f32 v246, v92, v93
	v_cvt_pk_bf16_f32 v247, v94, v95
	v_add_f32_e32 v88, v88, v170
	v_add_f32_e32 v89, v89, v171
	v_add_f32_e32 v90, v90, v172
	v_add_f32_e32 v91, v91, v173
	v_mul_f32_e32 v88, 0xbfb8aa3b, v88
	v_mul_f32_e32 v89, 0xbfb8aa3b, v89
	v_mul_f32_e32 v90, 0xbfb8aa3b, v90
	v_mul_f32_e32 v91, 0xbfb8aa3b, v91
	v_exp_f32_e32 v88, v88
	v_exp_f32_e32 v89, v89
	v_exp_f32_e32 v90, v90
	v_exp_f32_e32 v91, v91
	v_add_f32_e32 v88, 1.0, v88
	v_add_f32_e32 v89, 1.0, v89
	v_add_f32_e32 v90, 1.0, v90
	v_add_f32_e32 v91, 1.0, v91
	v_rcp_f32_e32 v88, v88
	v_rcp_f32_e32 v89, v89
	v_rcp_f32_e32 v90, v90
	v_rcp_f32_e32 v91, v91
	v_lshlrev_b32_e32 v156, 16, v200
	v_and_b32_e32 v157, 0xffff0000, v200
	v_lshlrev_b32_e32 v158, 16, v201
	v_and_b32_e32 v159, 0xffff0000, v201
	v_mul_f32_e32 v88, v88, v156
	v_mul_f32_e32 v89, v89, v157
	v_mul_f32_e32 v90, v90, v158
	v_mul_f32_e32 v91, v91, v159
	v_lshlrev_b32_e32 v156, 16, v232
	v_and_b32_e32 v157, 0xffff0000, v232
	v_lshlrev_b32_e32 v158, 16, v233
	v_and_b32_e32 v159, 0xffff0000, v233
	v_mul_f32_e32 v88, v88, v156
	v_mul_f32_e32 v89, v89, v157
	v_mul_f32_e32 v90, v90, v158
	v_mul_f32_e32 v91, v91, v159
	v_mul_f32_e32 v156, 0xbfb8aa3b, v156
	v_mul_f32_e32 v157, 0xbfb8aa3b, v157
	v_mul_f32_e32 v158, 0xbfb8aa3b, v158
	v_mul_f32_e32 v159, 0xbfb8aa3b, v159
	v_exp_f32_e32 v156, v156
	v_exp_f32_e32 v157, v157
	v_exp_f32_e32 v158, v158
	v_exp_f32_e32 v159, v159
	v_add_f32_e32 v156, 1.0, v156
	v_add_f32_e32 v157, 1.0, v157
	v_add_f32_e32 v158, 1.0, v158
	v_add_f32_e32 v159, 1.0, v159
	v_rcp_f32_e32 v156, v156
	v_rcp_f32_e32 v157, v157
	v_rcp_f32_e32 v158, v158
	v_rcp_f32_e32 v159, v159
	v_mul_f32_e32 v88, v156, v88
	v_mul_f32_e32 v89, v157, v89
	v_mul_f32_e32 v90, v158, v90
	v_mul_f32_e32 v91, v159, v91
	v_cvt_pk_bf16_f32 v248, v88, v89
	v_cvt_pk_bf16_f32 v249, v90, v91
	s_mov_b32 s38, 0x20000
	s_mov_b32 s39, 0
	v_lshl_add_u64 v[128:129], v[134:135], 0, s[38:39]
	global_store_dwordx4 v[128:129], v[246:249], off
	v_add_f32_e32 v84, v84, v174
	v_add_f32_e32 v85, v85, v175
	v_add_f32_e32 v86, v86, v176
	v_add_f32_e32 v87, v87, v177
	v_mul_f32_e32 v84, 0xbfb8aa3b, v84
	v_mul_f32_e32 v85, 0xbfb8aa3b, v85
	v_mul_f32_e32 v86, 0xbfb8aa3b, v86
	v_mul_f32_e32 v87, 0xbfb8aa3b, v87
	v_exp_f32_e32 v84, v84
	v_exp_f32_e32 v85, v85
	v_exp_f32_e32 v86, v86
	v_exp_f32_e32 v87, v87
	v_add_f32_e32 v84, 1.0, v84
	v_add_f32_e32 v85, 1.0, v85
	v_add_f32_e32 v86, 1.0, v86
	v_add_f32_e32 v87, 1.0, v87
	v_rcp_f32_e32 v84, v84
	v_rcp_f32_e32 v85, v85
	v_rcp_f32_e32 v86, v86
	v_rcp_f32_e32 v87, v87
	v_lshlrev_b32_e32 v156, 16, v202
	v_and_b32_e32 v157, 0xffff0000, v202
	v_lshlrev_b32_e32 v158, 16, v203
	v_and_b32_e32 v159, 0xffff0000, v203
	v_mul_f32_e32 v84, v84, v156
	v_mul_f32_e32 v85, v85, v157
	v_mul_f32_e32 v86, v86, v158
	v_mul_f32_e32 v87, v87, v159
	v_lshlrev_b32_e32 v156, 16, v234
	v_and_b32_e32 v157, 0xffff0000, v234
	v_lshlrev_b32_e32 v158, 16, v235
	v_and_b32_e32 v159, 0xffff0000, v235
	v_mul_f32_e32 v84, v84, v156
	v_mul_f32_e32 v85, v85, v157
	v_mul_f32_e32 v86, v86, v158
	v_mul_f32_e32 v87, v87, v159
	v_mul_f32_e32 v156, 0xbfb8aa3b, v156
	v_mul_f32_e32 v157, 0xbfb8aa3b, v157
	v_mul_f32_e32 v158, 0xbfb8aa3b, v158
	v_mul_f32_e32 v159, 0xbfb8aa3b, v159
	v_exp_f32_e32 v156, v156
	v_exp_f32_e32 v157, v157
	v_exp_f32_e32 v158, v158
	v_exp_f32_e32 v159, v159
	v_add_f32_e32 v156, 1.0, v156
	v_add_f32_e32 v157, 1.0, v157
	v_add_f32_e32 v158, 1.0, v158
	v_add_f32_e32 v159, 1.0, v159
	v_rcp_f32_e32 v156, v156
	v_rcp_f32_e32 v157, v157
	v_rcp_f32_e32 v158, v158
	v_rcp_f32_e32 v159, v159
	v_mul_f32_e32 v84, v156, v84
	v_mul_f32_e32 v85, v157, v85
	v_mul_f32_e32 v86, v158, v86
	v_mul_f32_e32 v87, v159, v87
	v_cvt_pk_bf16_f32 v250, v84, v85
	v_cvt_pk_bf16_f32 v251, v86, v87
	v_add_f32_e32 v80, v80, v178
	v_add_f32_e32 v81, v81, v179
	v_add_f32_e32 v82, v82, v180
	v_add_f32_e32 v83, v83, v181
	v_mul_f32_e32 v80, 0xbfb8aa3b, v80
	v_mul_f32_e32 v81, 0xbfb8aa3b, v81
	v_mul_f32_e32 v82, 0xbfb8aa3b, v82
	v_mul_f32_e32 v83, 0xbfb8aa3b, v83
	v_exp_f32_e32 v80, v80
	v_exp_f32_e32 v81, v81
	v_exp_f32_e32 v82, v82
	v_exp_f32_e32 v83, v83
	v_add_f32_e32 v80, 1.0, v80
	v_add_f32_e32 v81, 1.0, v81
	v_add_f32_e32 v82, 1.0, v82
	v_add_f32_e32 v83, 1.0, v83
	v_rcp_f32_e32 v80, v80
	v_rcp_f32_e32 v81, v81
	v_rcp_f32_e32 v82, v82
	v_rcp_f32_e32 v83, v83
	v_lshlrev_b32_e32 v156, 16, v204
	v_and_b32_e32 v157, 0xffff0000, v204
	v_lshlrev_b32_e32 v158, 16, v205
	v_and_b32_e32 v159, 0xffff0000, v205
	v_mul_f32_e32 v80, v80, v156
	v_mul_f32_e32 v81, v81, v157
	v_mul_f32_e32 v82, v82, v158
	v_mul_f32_e32 v83, v83, v159
	v_lshlrev_b32_e32 v156, 16, v236
	v_and_b32_e32 v157, 0xffff0000, v236
	v_lshlrev_b32_e32 v158, 16, v237
	v_and_b32_e32 v159, 0xffff0000, v237
	v_mul_f32_e32 v80, v80, v156
	v_mul_f32_e32 v81, v81, v157
	v_mul_f32_e32 v82, v82, v158
	v_mul_f32_e32 v83, v83, v159
	v_mul_f32_e32 v156, 0xbfb8aa3b, v156
	v_mul_f32_e32 v157, 0xbfb8aa3b, v157
	v_mul_f32_e32 v158, 0xbfb8aa3b, v158
	v_mul_f32_e32 v159, 0xbfb8aa3b, v159
	v_exp_f32_e32 v156, v156
	v_exp_f32_e32 v157, v157
	v_exp_f32_e32 v158, v158
	v_exp_f32_e32 v159, v159
	v_add_f32_e32 v156, 1.0, v156
	v_add_f32_e32 v157, 1.0, v157
	v_add_f32_e32 v158, 1.0, v158
	v_add_f32_e32 v159, 1.0, v159
	v_rcp_f32_e32 v156, v156
	v_rcp_f32_e32 v157, v157
	v_rcp_f32_e32 v158, v158
	v_rcp_f32_e32 v159, v159
	v_mul_f32_e32 v80, v156, v80
	v_mul_f32_e32 v81, v157, v81
	v_mul_f32_e32 v82, v158, v82
	v_mul_f32_e32 v83, v159, v83
	v_cvt_pk_bf16_f32 v252, v80, v81
	v_cvt_pk_bf16_f32 v253, v82, v83
	global_store_dwordx4 v[128:129], v[250:253], off offset:256
	s_mov_b32 s38, 0x1e0000
	s_mov_b32 s39, 0
	v_lshl_add_u64 v[128:129], v[130:131], 0, s[38:39]
	global_load_dwordx4 v[84:87], v[128:129], off
	global_load_dwordx4 v[80:83], v[128:129], off offset:256
	s_mov_b32 s38, 0x50000
	v_lshl_add_u64 v[128:129], v[132:133], 0, s[38:39]
	global_load_dwordx4 v[92:95], v[128:129], off
	global_load_dwordx4 v[88:91], v[128:129], off offset:256
	s_waitcnt vmcnt(18)
	v_add_f32_e32 v76, v76, v166
	v_add_f32_e32 v77, v77, v167
	v_add_f32_e32 v78, v78, v168
	v_add_f32_e32 v79, v79, v169
	v_mul_f32_e32 v76, 0xbfb8aa3b, v76
	v_mul_f32_e32 v77, 0xbfb8aa3b, v77
	v_mul_f32_e32 v78, 0xbfb8aa3b, v78
	v_mul_f32_e32 v79, 0xbfb8aa3b, v79
	v_exp_f32_e32 v76, v76
	v_exp_f32_e32 v77, v77
	v_exp_f32_e32 v78, v78
	v_exp_f32_e32 v79, v79
	v_add_f32_e32 v76, 1.0, v76
	v_add_f32_e32 v77, 1.0, v77
	v_add_f32_e32 v78, 1.0, v78
	v_add_f32_e32 v79, 1.0, v79
	v_rcp_f32_e32 v76, v76
	v_rcp_f32_e32 v77, v77
	v_rcp_f32_e32 v78, v78
	v_rcp_f32_e32 v79, v79
	v_lshlrev_b32_e32 v156, 16, v206
	v_and_b32_e32 v157, 0xffff0000, v206
	v_lshlrev_b32_e32 v158, 16, v207
	v_and_b32_e32 v159, 0xffff0000, v207
	v_mul_f32_e32 v76, v76, v156
	v_mul_f32_e32 v77, v77, v157
	v_mul_f32_e32 v78, v78, v158
	v_mul_f32_e32 v79, v79, v159
	v_lshlrev_b32_e32 v156, 16, v238
	v_and_b32_e32 v157, 0xffff0000, v238
	v_lshlrev_b32_e32 v158, 16, v239
	v_and_b32_e32 v159, 0xffff0000, v239
	v_mul_f32_e32 v76, v76, v156
	v_mul_f32_e32 v77, v77, v157
	v_mul_f32_e32 v78, v78, v158
	v_mul_f32_e32 v79, v79, v159
	v_mul_f32_e32 v156, 0xbfb8aa3b, v156
	v_mul_f32_e32 v157, 0xbfb8aa3b, v157
	v_mul_f32_e32 v158, 0xbfb8aa3b, v158
	v_mul_f32_e32 v159, 0xbfb8aa3b, v159
	v_exp_f32_e32 v156, v156
	v_exp_f32_e32 v157, v157
	v_exp_f32_e32 v158, v158
	v_exp_f32_e32 v159, v159
	v_add_f32_e32 v156, 1.0, v156
	v_add_f32_e32 v157, 1.0, v157
	v_add_f32_e32 v158, 1.0, v158
	v_add_f32_e32 v159, 1.0, v159
	v_rcp_f32_e32 v156, v156
	v_rcp_f32_e32 v157, v157
	v_rcp_f32_e32 v158, v158
	v_rcp_f32_e32 v159, v159
	v_mul_f32_e32 v76, v156, v76
	v_mul_f32_e32 v77, v157, v77
	v_mul_f32_e32 v78, v158, v78
	v_mul_f32_e32 v79, v159, v79
	v_cvt_pk_bf16_f32 v246, v76, v77
	v_cvt_pk_bf16_f32 v247, v78, v79
	v_add_f32_e32 v72, v72, v170
	v_add_f32_e32 v73, v73, v171
	v_add_f32_e32 v74, v74, v172
	v_add_f32_e32 v75, v75, v173
	v_mul_f32_e32 v72, 0xbfb8aa3b, v72
	v_mul_f32_e32 v73, 0xbfb8aa3b, v73
	v_mul_f32_e32 v74, 0xbfb8aa3b, v74
	v_mul_f32_e32 v75, 0xbfb8aa3b, v75
	v_exp_f32_e32 v72, v72
	v_exp_f32_e32 v73, v73
	v_exp_f32_e32 v74, v74
	v_exp_f32_e32 v75, v75
	v_add_f32_e32 v72, 1.0, v72
	v_add_f32_e32 v73, 1.0, v73
	v_add_f32_e32 v74, 1.0, v74
	v_add_f32_e32 v75, 1.0, v75
	v_rcp_f32_e32 v72, v72
	v_rcp_f32_e32 v73, v73
	v_rcp_f32_e32 v74, v74
	v_rcp_f32_e32 v75, v75
	v_lshlrev_b32_e32 v156, 16, v208
	v_and_b32_e32 v157, 0xffff0000, v208
	v_lshlrev_b32_e32 v158, 16, v209
	v_and_b32_e32 v159, 0xffff0000, v209
	v_mul_f32_e32 v72, v72, v156
	v_mul_f32_e32 v73, v73, v157
	v_mul_f32_e32 v74, v74, v158
	v_mul_f32_e32 v75, v75, v159
	v_lshlrev_b32_e32 v156, 16, v240
	v_and_b32_e32 v157, 0xffff0000, v240
	v_lshlrev_b32_e32 v158, 16, v241
	v_and_b32_e32 v159, 0xffff0000, v241
	v_mul_f32_e32 v72, v72, v156
	v_mul_f32_e32 v73, v73, v157
	v_mul_f32_e32 v74, v74, v158
	v_mul_f32_e32 v75, v75, v159
	v_mul_f32_e32 v156, 0xbfb8aa3b, v156
	v_mul_f32_e32 v157, 0xbfb8aa3b, v157
	v_mul_f32_e32 v158, 0xbfb8aa3b, v158
	v_mul_f32_e32 v159, 0xbfb8aa3b, v159
	v_exp_f32_e32 v156, v156
	v_exp_f32_e32 v157, v157
	v_exp_f32_e32 v158, v158
	v_exp_f32_e32 v159, v159
	v_add_f32_e32 v156, 1.0, v156
	v_add_f32_e32 v157, 1.0, v157
	v_add_f32_e32 v158, 1.0, v158
	v_add_f32_e32 v159, 1.0, v159
	v_rcp_f32_e32 v156, v156
	v_rcp_f32_e32 v157, v157
	v_rcp_f32_e32 v158, v158
	v_rcp_f32_e32 v159, v159
	v_mul_f32_e32 v72, v156, v72
	v_mul_f32_e32 v73, v157, v73
	v_mul_f32_e32 v74, v158, v74
	v_mul_f32_e32 v75, v159, v75
	v_cvt_pk_bf16_f32 v248, v72, v73
	v_cvt_pk_bf16_f32 v249, v74, v75
	s_mov_b32 s38, 0x30000
	s_mov_b32 s39, 0
	v_lshl_add_u64 v[128:129], v[134:135], 0, s[38:39]
	global_store_dwordx4 v[128:129], v[246:249], off
	v_add_f32_e32 v68, v68, v174
	v_add_f32_e32 v69, v69, v175
	v_add_f32_e32 v70, v70, v176
	v_add_f32_e32 v71, v71, v177
	v_mul_f32_e32 v68, 0xbfb8aa3b, v68
	v_mul_f32_e32 v69, 0xbfb8aa3b, v69
	v_mul_f32_e32 v70, 0xbfb8aa3b, v70
	v_mul_f32_e32 v71, 0xbfb8aa3b, v71
	v_exp_f32_e32 v68, v68
	v_exp_f32_e32 v69, v69
	v_exp_f32_e32 v70, v70
	v_exp_f32_e32 v71, v71
	v_add_f32_e32 v68, 1.0, v68
	v_add_f32_e32 v69, 1.0, v69
	v_add_f32_e32 v70, 1.0, v70
	v_add_f32_e32 v71, 1.0, v71
	v_rcp_f32_e32 v68, v68
	v_rcp_f32_e32 v69, v69
	v_rcp_f32_e32 v70, v70
	v_rcp_f32_e32 v71, v71
	v_lshlrev_b32_e32 v156, 16, v210
	v_and_b32_e32 v157, 0xffff0000, v210
	v_lshlrev_b32_e32 v158, 16, v211
	v_and_b32_e32 v159, 0xffff0000, v211
	v_mul_f32_e32 v68, v68, v156
	v_mul_f32_e32 v69, v69, v157
	v_mul_f32_e32 v70, v70, v158
	v_mul_f32_e32 v71, v71, v159
	v_lshlrev_b32_e32 v156, 16, v242
	v_and_b32_e32 v157, 0xffff0000, v242
	v_lshlrev_b32_e32 v158, 16, v243
	v_and_b32_e32 v159, 0xffff0000, v243
	v_mul_f32_e32 v68, v68, v156
	v_mul_f32_e32 v69, v69, v157
	v_mul_f32_e32 v70, v70, v158
	v_mul_f32_e32 v71, v71, v159
	v_mul_f32_e32 v156, 0xbfb8aa3b, v156
	v_mul_f32_e32 v157, 0xbfb8aa3b, v157
	v_mul_f32_e32 v158, 0xbfb8aa3b, v158
	v_mul_f32_e32 v159, 0xbfb8aa3b, v159
	v_exp_f32_e32 v156, v156
	v_exp_f32_e32 v157, v157
	v_exp_f32_e32 v158, v158
	v_exp_f32_e32 v159, v159
	v_add_f32_e32 v156, 1.0, v156
	v_add_f32_e32 v157, 1.0, v157
	v_add_f32_e32 v158, 1.0, v158
	v_add_f32_e32 v159, 1.0, v159
	v_rcp_f32_e32 v156, v156
	v_rcp_f32_e32 v157, v157
	v_rcp_f32_e32 v158, v158
	v_rcp_f32_e32 v159, v159
	v_mul_f32_e32 v68, v156, v68
	v_mul_f32_e32 v69, v157, v69
	v_mul_f32_e32 v70, v158, v70
	v_mul_f32_e32 v71, v159, v71
	v_cvt_pk_bf16_f32 v250, v68, v69
	v_cvt_pk_bf16_f32 v251, v70, v71
	v_add_f32_e32 v64, v64, v178
	v_add_f32_e32 v65, v65, v179
	v_add_f32_e32 v66, v66, v180
	v_add_f32_e32 v67, v67, v181
	v_mul_f32_e32 v64, 0xbfb8aa3b, v64
	v_mul_f32_e32 v65, 0xbfb8aa3b, v65
	v_mul_f32_e32 v66, 0xbfb8aa3b, v66
	v_mul_f32_e32 v67, 0xbfb8aa3b, v67
	v_exp_f32_e32 v64, v64
	v_exp_f32_e32 v65, v65
	v_exp_f32_e32 v66, v66
	v_exp_f32_e32 v67, v67
	v_add_f32_e32 v64, 1.0, v64
	v_add_f32_e32 v65, 1.0, v65
	v_add_f32_e32 v66, 1.0, v66
	v_add_f32_e32 v67, 1.0, v67
	v_rcp_f32_e32 v64, v64
	v_rcp_f32_e32 v65, v65
	v_rcp_f32_e32 v66, v66
	v_rcp_f32_e32 v67, v67
	v_lshlrev_b32_e32 v156, 16, v212
	v_and_b32_e32 v157, 0xffff0000, v212
	v_lshlrev_b32_e32 v158, 16, v213
	v_and_b32_e32 v159, 0xffff0000, v213
	v_mul_f32_e32 v64, v64, v156
	v_mul_f32_e32 v65, v65, v157
	v_mul_f32_e32 v66, v66, v158
	v_mul_f32_e32 v67, v67, v159
	v_lshlrev_b32_e32 v156, 16, v244
	v_and_b32_e32 v157, 0xffff0000, v244
	v_lshlrev_b32_e32 v158, 16, v245
	v_and_b32_e32 v159, 0xffff0000, v245
	v_mul_f32_e32 v64, v64, v156
	v_mul_f32_e32 v65, v65, v157
	v_mul_f32_e32 v66, v66, v158
	v_mul_f32_e32 v67, v67, v159
	v_mul_f32_e32 v156, 0xbfb8aa3b, v156
	v_mul_f32_e32 v157, 0xbfb8aa3b, v157
	v_mul_f32_e32 v158, 0xbfb8aa3b, v158
	v_mul_f32_e32 v159, 0xbfb8aa3b, v159
	v_exp_f32_e32 v156, v156
	v_exp_f32_e32 v157, v157
	v_exp_f32_e32 v158, v158
	v_exp_f32_e32 v159, v159
	v_add_f32_e32 v156, 1.0, v156
	v_add_f32_e32 v157, 1.0, v157
	v_add_f32_e32 v158, 1.0, v158
	v_add_f32_e32 v159, 1.0, v159
	v_rcp_f32_e32 v156, v156
	v_rcp_f32_e32 v157, v157
	v_rcp_f32_e32 v158, v158
	v_rcp_f32_e32 v159, v159
	v_mul_f32_e32 v64, v156, v64
	v_mul_f32_e32 v65, v157, v65
	v_mul_f32_e32 v66, v158, v66
	v_mul_f32_e32 v67, v159, v67
	v_cvt_pk_bf16_f32 v252, v64, v65
	v_cvt_pk_bf16_f32 v253, v66, v67
	global_store_dwordx4 v[128:129], v[250:253], off offset:256
	s_mov_b32 s38, 0x210000
	s_mov_b32 s39, 0
	v_lshl_add_u64 v[128:129], v[130:131], 0, s[38:39]
	global_load_dwordx4 v[68:71], v[128:129], off
	global_load_dwordx4 v[64:67], v[128:129], off offset:256
	s_mov_b32 s38, 0x58000
	v_lshl_add_u64 v[128:129], v[132:133], 0, s[38:39]
	global_load_dwordx4 v[76:79], v[128:129], off
	global_load_dwordx4 v[72:75], v[128:129], off offset:256
	s_waitcnt vmcnt(18)
	v_add_f32_e32 v60, v60, v166
	v_add_f32_e32 v61, v61, v167
	v_add_f32_e32 v62, v62, v168
	v_add_f32_e32 v63, v63, v169
	v_mul_f32_e32 v60, 0xbfb8aa3b, v60
	v_mul_f32_e32 v61, 0xbfb8aa3b, v61
	v_mul_f32_e32 v62, 0xbfb8aa3b, v62
	v_mul_f32_e32 v63, 0xbfb8aa3b, v63
	v_exp_f32_e32 v60, v60
	v_exp_f32_e32 v61, v61
	v_exp_f32_e32 v62, v62
	v_exp_f32_e32 v63, v63
	v_add_f32_e32 v60, 1.0, v60
	v_add_f32_e32 v61, 1.0, v61
	v_add_f32_e32 v62, 1.0, v62
	v_add_f32_e32 v63, 1.0, v63
	v_rcp_f32_e32 v60, v60
	v_rcp_f32_e32 v61, v61
	v_rcp_f32_e32 v62, v62
	v_rcp_f32_e32 v63, v63
	v_lshlrev_b32_e32 v156, 16, v124
	v_and_b32_e32 v157, 0xffff0000, v124
	v_lshlrev_b32_e32 v158, 16, v125
	v_and_b32_e32 v159, 0xffff0000, v125
	v_mul_f32_e32 v60, v60, v156
	v_mul_f32_e32 v61, v61, v157
	v_mul_f32_e32 v62, v62, v158
	v_mul_f32_e32 v63, v63, v159
	v_lshlrev_b32_e32 v156, 16, v116
	v_and_b32_e32 v157, 0xffff0000, v116
	v_lshlrev_b32_e32 v158, 16, v117
	v_and_b32_e32 v159, 0xffff0000, v117
	v_mul_f32_e32 v60, v60, v156
	v_mul_f32_e32 v61, v61, v157
	v_mul_f32_e32 v62, v62, v158
	v_mul_f32_e32 v63, v63, v159
	v_mul_f32_e32 v156, 0xbfb8aa3b, v156
	v_mul_f32_e32 v157, 0xbfb8aa3b, v157
	v_mul_f32_e32 v158, 0xbfb8aa3b, v158
	v_mul_f32_e32 v159, 0xbfb8aa3b, v159
	v_exp_f32_e32 v156, v156
	v_exp_f32_e32 v157, v157
	v_exp_f32_e32 v158, v158
	v_exp_f32_e32 v159, v159
	v_add_f32_e32 v156, 1.0, v156
	v_add_f32_e32 v157, 1.0, v157
	v_add_f32_e32 v158, 1.0, v158
	v_add_f32_e32 v159, 1.0, v159
	v_rcp_f32_e32 v156, v156
	v_rcp_f32_e32 v157, v157
	v_rcp_f32_e32 v158, v158
	v_rcp_f32_e32 v159, v159
	v_mul_f32_e32 v60, v156, v60
	v_mul_f32_e32 v61, v157, v61
	v_mul_f32_e32 v62, v158, v62
	v_mul_f32_e32 v63, v159, v63
	v_cvt_pk_bf16_f32 v246, v60, v61
	v_cvt_pk_bf16_f32 v247, v62, v63
	v_add_f32_e32 v56, v56, v170
	v_add_f32_e32 v57, v57, v171
	v_add_f32_e32 v58, v58, v172
	v_add_f32_e32 v59, v59, v173
	v_mul_f32_e32 v56, 0xbfb8aa3b, v56
	v_mul_f32_e32 v57, 0xbfb8aa3b, v57
	v_mul_f32_e32 v58, 0xbfb8aa3b, v58
	v_mul_f32_e32 v59, 0xbfb8aa3b, v59
	v_exp_f32_e32 v56, v56
	v_exp_f32_e32 v57, v57
	v_exp_f32_e32 v58, v58
	v_exp_f32_e32 v59, v59
	v_add_f32_e32 v56, 1.0, v56
	v_add_f32_e32 v57, 1.0, v57
	v_add_f32_e32 v58, 1.0, v58
	v_add_f32_e32 v59, 1.0, v59
	v_rcp_f32_e32 v56, v56
	v_rcp_f32_e32 v57, v57
	v_rcp_f32_e32 v58, v58
	v_rcp_f32_e32 v59, v59
	v_lshlrev_b32_e32 v156, 16, v126
	v_and_b32_e32 v157, 0xffff0000, v126
	v_lshlrev_b32_e32 v158, 16, v127
	v_and_b32_e32 v159, 0xffff0000, v127
	v_mul_f32_e32 v56, v56, v156
	v_mul_f32_e32 v57, v57, v157
	v_mul_f32_e32 v58, v58, v158
	v_mul_f32_e32 v59, v59, v159
	v_lshlrev_b32_e32 v156, 16, v118
	v_and_b32_e32 v157, 0xffff0000, v118
	v_lshlrev_b32_e32 v158, 16, v119
	v_and_b32_e32 v159, 0xffff0000, v119
	v_mul_f32_e32 v56, v56, v156
	v_mul_f32_e32 v57, v57, v157
	v_mul_f32_e32 v58, v58, v158
	v_mul_f32_e32 v59, v59, v159
	v_mul_f32_e32 v156, 0xbfb8aa3b, v156
	v_mul_f32_e32 v157, 0xbfb8aa3b, v157
	v_mul_f32_e32 v158, 0xbfb8aa3b, v158
	v_mul_f32_e32 v159, 0xbfb8aa3b, v159
	v_exp_f32_e32 v156, v156
	v_exp_f32_e32 v157, v157
	v_exp_f32_e32 v158, v158
	v_exp_f32_e32 v159, v159
	v_add_f32_e32 v156, 1.0, v156
	v_add_f32_e32 v157, 1.0, v157
	v_add_f32_e32 v158, 1.0, v158
	v_add_f32_e32 v159, 1.0, v159
	v_rcp_f32_e32 v156, v156
	v_rcp_f32_e32 v157, v157
	v_rcp_f32_e32 v158, v158
	v_rcp_f32_e32 v159, v159
	v_mul_f32_e32 v56, v156, v56
	v_mul_f32_e32 v57, v157, v57
	v_mul_f32_e32 v58, v158, v58
	v_mul_f32_e32 v59, v159, v59
	v_cvt_pk_bf16_f32 v248, v56, v57
	v_cvt_pk_bf16_f32 v249, v58, v59
	s_mov_b32 s38, 0x80000
	s_mov_b32 s39, 0
	v_lshl_add_u64 v[128:129], v[134:135], 0, s[38:39]
	global_store_dwordx4 v[128:129], v[246:249], off
	v_add_f32_e32 v52, v52, v174
	v_add_f32_e32 v53, v53, v175
	v_add_f32_e32 v54, v54, v176
	v_add_f32_e32 v55, v55, v177
	v_mul_f32_e32 v52, 0xbfb8aa3b, v52
	v_mul_f32_e32 v53, 0xbfb8aa3b, v53
	v_mul_f32_e32 v54, 0xbfb8aa3b, v54
	v_mul_f32_e32 v55, 0xbfb8aa3b, v55
	v_exp_f32_e32 v52, v52
	v_exp_f32_e32 v53, v53
	v_exp_f32_e32 v54, v54
	v_exp_f32_e32 v55, v55
	v_add_f32_e32 v52, 1.0, v52
	v_add_f32_e32 v53, 1.0, v53
	v_add_f32_e32 v54, 1.0, v54
	v_add_f32_e32 v55, 1.0, v55
	v_rcp_f32_e32 v52, v52
	v_rcp_f32_e32 v53, v53
	v_rcp_f32_e32 v54, v54
	v_rcp_f32_e32 v55, v55
	v_lshlrev_b32_e32 v156, 16, v120
	v_and_b32_e32 v157, 0xffff0000, v120
	v_lshlrev_b32_e32 v158, 16, v121
	v_and_b32_e32 v159, 0xffff0000, v121
	v_mul_f32_e32 v52, v52, v156
	v_mul_f32_e32 v53, v53, v157
	v_mul_f32_e32 v54, v54, v158
	v_mul_f32_e32 v55, v55, v159
	v_lshlrev_b32_e32 v156, 16, v112
	v_and_b32_e32 v157, 0xffff0000, v112
	v_lshlrev_b32_e32 v158, 16, v113
	v_and_b32_e32 v159, 0xffff0000, v113
	v_mul_f32_e32 v52, v52, v156
	v_mul_f32_e32 v53, v53, v157
	v_mul_f32_e32 v54, v54, v158
	v_mul_f32_e32 v55, v55, v159
	v_mul_f32_e32 v156, 0xbfb8aa3b, v156
	v_mul_f32_e32 v157, 0xbfb8aa3b, v157
	v_mul_f32_e32 v158, 0xbfb8aa3b, v158
	v_mul_f32_e32 v159, 0xbfb8aa3b, v159
	v_exp_f32_e32 v156, v156
	v_exp_f32_e32 v157, v157
	v_exp_f32_e32 v158, v158
	v_exp_f32_e32 v159, v159
	v_add_f32_e32 v156, 1.0, v156
	v_add_f32_e32 v157, 1.0, v157
	v_add_f32_e32 v158, 1.0, v158
	v_add_f32_e32 v159, 1.0, v159
	v_rcp_f32_e32 v156, v156
	v_rcp_f32_e32 v157, v157
	v_rcp_f32_e32 v158, v158
	v_rcp_f32_e32 v159, v159
	v_mul_f32_e32 v52, v156, v52
	v_mul_f32_e32 v53, v157, v53
	v_mul_f32_e32 v54, v158, v54
	v_mul_f32_e32 v55, v159, v55
	v_cvt_pk_bf16_f32 v250, v52, v53
	v_cvt_pk_bf16_f32 v251, v54, v55
	v_add_f32_e32 v48, v48, v178
	v_add_f32_e32 v49, v49, v179
	v_add_f32_e32 v50, v50, v180
	v_add_f32_e32 v51, v51, v181
	v_mul_f32_e32 v48, 0xbfb8aa3b, v48
	v_mul_f32_e32 v49, 0xbfb8aa3b, v49
	v_mul_f32_e32 v50, 0xbfb8aa3b, v50
	v_mul_f32_e32 v51, 0xbfb8aa3b, v51
	v_exp_f32_e32 v48, v48
	v_exp_f32_e32 v49, v49
	v_exp_f32_e32 v50, v50
	v_exp_f32_e32 v51, v51
	v_add_f32_e32 v48, 1.0, v48
	v_add_f32_e32 v49, 1.0, v49
	v_add_f32_e32 v50, 1.0, v50
	v_add_f32_e32 v51, 1.0, v51
	v_rcp_f32_e32 v48, v48
	v_rcp_f32_e32 v49, v49
	v_rcp_f32_e32 v50, v50
	v_rcp_f32_e32 v51, v51
	v_lshlrev_b32_e32 v156, 16, v122
	v_and_b32_e32 v157, 0xffff0000, v122
	v_lshlrev_b32_e32 v158, 16, v123
	v_and_b32_e32 v159, 0xffff0000, v123
	v_mul_f32_e32 v48, v48, v156
	v_mul_f32_e32 v49, v49, v157
	v_mul_f32_e32 v50, v50, v158
	v_mul_f32_e32 v51, v51, v159
	v_lshlrev_b32_e32 v156, 16, v114
	v_and_b32_e32 v157, 0xffff0000, v114
	v_lshlrev_b32_e32 v158, 16, v115
	v_and_b32_e32 v159, 0xffff0000, v115
	v_mul_f32_e32 v48, v48, v156
	v_mul_f32_e32 v49, v49, v157
	v_mul_f32_e32 v50, v50, v158
	v_mul_f32_e32 v51, v51, v159
	v_mul_f32_e32 v156, 0xbfb8aa3b, v156
	v_mul_f32_e32 v157, 0xbfb8aa3b, v157
	v_mul_f32_e32 v158, 0xbfb8aa3b, v158
	v_mul_f32_e32 v159, 0xbfb8aa3b, v159
	v_exp_f32_e32 v156, v156
	v_exp_f32_e32 v157, v157
	v_exp_f32_e32 v158, v158
	v_exp_f32_e32 v159, v159
	v_add_f32_e32 v156, 1.0, v156
	v_add_f32_e32 v157, 1.0, v157
	v_add_f32_e32 v158, 1.0, v158
	v_add_f32_e32 v159, 1.0, v159
	v_rcp_f32_e32 v156, v156
	v_rcp_f32_e32 v157, v157
	v_rcp_f32_e32 v158, v158
	v_rcp_f32_e32 v159, v159
	v_mul_f32_e32 v48, v156, v48
	v_mul_f32_e32 v49, v157, v49
	v_mul_f32_e32 v50, v158, v50
	v_mul_f32_e32 v51, v159, v51
	v_cvt_pk_bf16_f32 v252, v48, v49
	v_cvt_pk_bf16_f32 v253, v50, v51
	global_store_dwordx4 v[128:129], v[250:253], off offset:256
	s_waitcnt vmcnt(14)
	v_add_f32_e32 v44, v44, v166
	v_add_f32_e32 v45, v45, v167
	v_add_f32_e32 v46, v46, v168
	v_add_f32_e32 v47, v47, v169
	v_mul_f32_e32 v44, 0xbfb8aa3b, v44
	v_mul_f32_e32 v45, 0xbfb8aa3b, v45
	v_mul_f32_e32 v46, 0xbfb8aa3b, v46
	v_mul_f32_e32 v47, 0xbfb8aa3b, v47
	v_exp_f32_e32 v44, v44
	v_exp_f32_e32 v45, v45
	v_exp_f32_e32 v46, v46
	v_exp_f32_e32 v47, v47
	v_add_f32_e32 v44, 1.0, v44
	v_add_f32_e32 v45, 1.0, v45
	v_add_f32_e32 v46, 1.0, v46
	v_add_f32_e32 v47, 1.0, v47
	v_rcp_f32_e32 v44, v44
	v_rcp_f32_e32 v45, v45
	v_rcp_f32_e32 v46, v46
	v_rcp_f32_e32 v47, v47
	v_lshlrev_b32_e32 v156, 16, v108
	v_and_b32_e32 v157, 0xffff0000, v108
	v_lshlrev_b32_e32 v158, 16, v109
	v_and_b32_e32 v159, 0xffff0000, v109
	v_mul_f32_e32 v44, v44, v156
	v_mul_f32_e32 v45, v45, v157
	v_mul_f32_e32 v46, v46, v158
	v_mul_f32_e32 v47, v47, v159
	v_lshlrev_b32_e32 v156, 16, v100
	v_and_b32_e32 v157, 0xffff0000, v100
	v_lshlrev_b32_e32 v158, 16, v101
	v_and_b32_e32 v159, 0xffff0000, v101
	v_mul_f32_e32 v44, v44, v156
	v_mul_f32_e32 v45, v45, v157
	v_mul_f32_e32 v46, v46, v158
	v_mul_f32_e32 v47, v47, v159
	v_mul_f32_e32 v156, 0xbfb8aa3b, v156
	v_mul_f32_e32 v157, 0xbfb8aa3b, v157
	v_mul_f32_e32 v158, 0xbfb8aa3b, v158
	v_mul_f32_e32 v159, 0xbfb8aa3b, v159
	v_exp_f32_e32 v156, v156
	v_exp_f32_e32 v157, v157
	v_exp_f32_e32 v158, v158
	v_exp_f32_e32 v159, v159
	v_add_f32_e32 v156, 1.0, v156
	v_add_f32_e32 v157, 1.0, v157
	v_add_f32_e32 v158, 1.0, v158
	v_add_f32_e32 v159, 1.0, v159
	v_rcp_f32_e32 v156, v156
	v_rcp_f32_e32 v157, v157
	v_rcp_f32_e32 v158, v158
	v_rcp_f32_e32 v159, v159
	v_mul_f32_e32 v44, v156, v44
	v_mul_f32_e32 v45, v157, v45
	v_mul_f32_e32 v46, v158, v46
	v_mul_f32_e32 v47, v159, v47
	v_cvt_pk_bf16_f32 v246, v44, v45
	v_cvt_pk_bf16_f32 v247, v46, v47
	v_add_f32_e32 v40, v40, v170
	v_add_f32_e32 v41, v41, v171
	v_add_f32_e32 v42, v42, v172
	v_add_f32_e32 v43, v43, v173
	v_mul_f32_e32 v40, 0xbfb8aa3b, v40
	v_mul_f32_e32 v41, 0xbfb8aa3b, v41
	v_mul_f32_e32 v42, 0xbfb8aa3b, v42
	v_mul_f32_e32 v43, 0xbfb8aa3b, v43
	v_exp_f32_e32 v40, v40
	v_exp_f32_e32 v41, v41
	v_exp_f32_e32 v42, v42
	v_exp_f32_e32 v43, v43
	v_add_f32_e32 v40, 1.0, v40
	v_add_f32_e32 v41, 1.0, v41
	v_add_f32_e32 v42, 1.0, v42
	v_add_f32_e32 v43, 1.0, v43
	v_rcp_f32_e32 v40, v40
	v_rcp_f32_e32 v41, v41
	v_rcp_f32_e32 v42, v42
	v_rcp_f32_e32 v43, v43
	v_lshlrev_b32_e32 v156, 16, v110
	v_and_b32_e32 v157, 0xffff0000, v110
	v_lshlrev_b32_e32 v158, 16, v111
	v_and_b32_e32 v159, 0xffff0000, v111
	v_mul_f32_e32 v40, v40, v156
	v_mul_f32_e32 v41, v41, v157
	v_mul_f32_e32 v42, v42, v158
	v_mul_f32_e32 v43, v43, v159
	v_lshlrev_b32_e32 v156, 16, v102
	v_and_b32_e32 v157, 0xffff0000, v102
	v_lshlrev_b32_e32 v158, 16, v103
	v_and_b32_e32 v159, 0xffff0000, v103
	v_mul_f32_e32 v40, v40, v156
	v_mul_f32_e32 v41, v41, v157
	v_mul_f32_e32 v42, v42, v158
	v_mul_f32_e32 v43, v43, v159
	v_mul_f32_e32 v156, 0xbfb8aa3b, v156
	v_mul_f32_e32 v157, 0xbfb8aa3b, v157
	v_mul_f32_e32 v158, 0xbfb8aa3b, v158
	v_mul_f32_e32 v159, 0xbfb8aa3b, v159
	v_exp_f32_e32 v156, v156
	v_exp_f32_e32 v157, v157
	v_exp_f32_e32 v158, v158
	v_exp_f32_e32 v159, v159
	v_add_f32_e32 v156, 1.0, v156
	v_add_f32_e32 v157, 1.0, v157
	v_add_f32_e32 v158, 1.0, v158
	v_add_f32_e32 v159, 1.0, v159
	v_rcp_f32_e32 v156, v156
	v_rcp_f32_e32 v157, v157
	v_rcp_f32_e32 v158, v158
	v_rcp_f32_e32 v159, v159
	v_mul_f32_e32 v40, v156, v40
	v_mul_f32_e32 v41, v157, v41
	v_mul_f32_e32 v42, v158, v42
	v_mul_f32_e32 v43, v159, v43
	v_cvt_pk_bf16_f32 v248, v40, v41
	v_cvt_pk_bf16_f32 v249, v42, v43
	s_mov_b32 s38, 0x90000
	s_mov_b32 s39, 0
	v_lshl_add_u64 v[128:129], v[134:135], 0, s[38:39]
	global_store_dwordx4 v[128:129], v[246:249], off
	v_add_f32_e32 v36, v36, v174
	v_add_f32_e32 v37, v37, v175
	v_add_f32_e32 v38, v38, v176
	v_add_f32_e32 v39, v39, v177
	v_mul_f32_e32 v36, 0xbfb8aa3b, v36
	v_mul_f32_e32 v37, 0xbfb8aa3b, v37
	v_mul_f32_e32 v38, 0xbfb8aa3b, v38
	v_mul_f32_e32 v39, 0xbfb8aa3b, v39
	v_exp_f32_e32 v36, v36
	v_exp_f32_e32 v37, v37
	v_exp_f32_e32 v38, v38
	v_exp_f32_e32 v39, v39
	v_add_f32_e32 v36, 1.0, v36
	v_add_f32_e32 v37, 1.0, v37
	v_add_f32_e32 v38, 1.0, v38
	v_add_f32_e32 v39, 1.0, v39
	v_rcp_f32_e32 v36, v36
	v_rcp_f32_e32 v37, v37
	v_rcp_f32_e32 v38, v38
	v_rcp_f32_e32 v39, v39
	v_lshlrev_b32_e32 v156, 16, v104
	v_and_b32_e32 v157, 0xffff0000, v104
	v_lshlrev_b32_e32 v158, 16, v105
	v_and_b32_e32 v159, 0xffff0000, v105
	v_mul_f32_e32 v36, v36, v156
	v_mul_f32_e32 v37, v37, v157
	v_mul_f32_e32 v38, v38, v158
	v_mul_f32_e32 v39, v39, v159
	v_lshlrev_b32_e32 v156, 16, v96
	v_and_b32_e32 v157, 0xffff0000, v96
	v_lshlrev_b32_e32 v158, 16, v97
	v_and_b32_e32 v159, 0xffff0000, v97
	v_mul_f32_e32 v36, v36, v156
	v_mul_f32_e32 v37, v37, v157
	v_mul_f32_e32 v38, v38, v158
	v_mul_f32_e32 v39, v39, v159
	v_mul_f32_e32 v156, 0xbfb8aa3b, v156
	v_mul_f32_e32 v157, 0xbfb8aa3b, v157
	v_mul_f32_e32 v158, 0xbfb8aa3b, v158
	v_mul_f32_e32 v159, 0xbfb8aa3b, v159
	v_exp_f32_e32 v156, v156
	v_exp_f32_e32 v157, v157
	v_exp_f32_e32 v158, v158
	v_exp_f32_e32 v159, v159
	v_add_f32_e32 v156, 1.0, v156
	v_add_f32_e32 v157, 1.0, v157
	v_add_f32_e32 v158, 1.0, v158
	v_add_f32_e32 v159, 1.0, v159
	v_rcp_f32_e32 v156, v156
	v_rcp_f32_e32 v157, v157
	v_rcp_f32_e32 v158, v158
	v_rcp_f32_e32 v159, v159
	v_mul_f32_e32 v36, v156, v36
	v_mul_f32_e32 v37, v157, v37
	v_mul_f32_e32 v38, v158, v38
	v_mul_f32_e32 v39, v159, v39
	v_cvt_pk_bf16_f32 v250, v36, v37
	v_cvt_pk_bf16_f32 v251, v38, v39
	v_add_f32_e32 v32, v32, v178
	v_add_f32_e32 v33, v33, v179
	v_add_f32_e32 v34, v34, v180
	v_add_f32_e32 v35, v35, v181
	v_mul_f32_e32 v32, 0xbfb8aa3b, v32
	v_mul_f32_e32 v33, 0xbfb8aa3b, v33
	v_mul_f32_e32 v34, 0xbfb8aa3b, v34
	v_mul_f32_e32 v35, 0xbfb8aa3b, v35
	v_exp_f32_e32 v32, v32
	v_exp_f32_e32 v33, v33
	v_exp_f32_e32 v34, v34
	v_exp_f32_e32 v35, v35
	v_add_f32_e32 v32, 1.0, v32
	v_add_f32_e32 v33, 1.0, v33
	v_add_f32_e32 v34, 1.0, v34
	v_add_f32_e32 v35, 1.0, v35
	v_rcp_f32_e32 v32, v32
	v_rcp_f32_e32 v33, v33
	v_rcp_f32_e32 v34, v34
	v_rcp_f32_e32 v35, v35
	v_lshlrev_b32_e32 v156, 16, v106
	v_and_b32_e32 v157, 0xffff0000, v106
	v_lshlrev_b32_e32 v158, 16, v107
	v_and_b32_e32 v159, 0xffff0000, v107
	v_mul_f32_e32 v32, v32, v156
	v_mul_f32_e32 v33, v33, v157
	v_mul_f32_e32 v34, v34, v158
	v_mul_f32_e32 v35, v35, v159
	v_lshlrev_b32_e32 v156, 16, v98
	v_and_b32_e32 v157, 0xffff0000, v98
	v_lshlrev_b32_e32 v158, 16, v99
	v_and_b32_e32 v159, 0xffff0000, v99
	v_mul_f32_e32 v32, v32, v156
	v_mul_f32_e32 v33, v33, v157
	v_mul_f32_e32 v34, v34, v158
	v_mul_f32_e32 v35, v35, v159
	v_mul_f32_e32 v156, 0xbfb8aa3b, v156
	v_mul_f32_e32 v157, 0xbfb8aa3b, v157
	v_mul_f32_e32 v158, 0xbfb8aa3b, v158
	v_mul_f32_e32 v159, 0xbfb8aa3b, v159
	v_exp_f32_e32 v156, v156
	v_exp_f32_e32 v157, v157
	v_exp_f32_e32 v158, v158
	v_exp_f32_e32 v159, v159
	v_add_f32_e32 v156, 1.0, v156
	v_add_f32_e32 v157, 1.0, v157
	v_add_f32_e32 v158, 1.0, v158
	v_add_f32_e32 v159, 1.0, v159
	v_rcp_f32_e32 v156, v156
	v_rcp_f32_e32 v157, v157
	v_rcp_f32_e32 v158, v158
	v_rcp_f32_e32 v159, v159
	v_mul_f32_e32 v32, v156, v32
	v_mul_f32_e32 v33, v157, v33
	v_mul_f32_e32 v34, v158, v34
	v_mul_f32_e32 v35, v159, v35
	v_cvt_pk_bf16_f32 v252, v32, v33
	v_cvt_pk_bf16_f32 v253, v34, v35
	global_store_dwordx4 v[128:129], v[250:253], off offset:256
	s_waitcnt vmcnt(10)
	v_add_f32_e32 v28, v28, v166
	v_add_f32_e32 v29, v29, v167
	v_add_f32_e32 v30, v30, v168
	v_add_f32_e32 v31, v31, v169
	v_mul_f32_e32 v28, 0xbfb8aa3b, v28
	v_mul_f32_e32 v29, 0xbfb8aa3b, v29
	v_mul_f32_e32 v30, 0xbfb8aa3b, v30
	v_mul_f32_e32 v31, 0xbfb8aa3b, v31
	v_exp_f32_e32 v28, v28
	v_exp_f32_e32 v29, v29
	v_exp_f32_e32 v30, v30
	v_exp_f32_e32 v31, v31
	v_add_f32_e32 v28, 1.0, v28
	v_add_f32_e32 v29, 1.0, v29
	v_add_f32_e32 v30, 1.0, v30
	v_add_f32_e32 v31, 1.0, v31
	v_rcp_f32_e32 v28, v28
	v_rcp_f32_e32 v29, v29
	v_rcp_f32_e32 v30, v30
	v_rcp_f32_e32 v31, v31
	v_lshlrev_b32_e32 v156, 16, v92
	v_and_b32_e32 v157, 0xffff0000, v92
	v_lshlrev_b32_e32 v158, 16, v93
	v_and_b32_e32 v159, 0xffff0000, v93
	v_mul_f32_e32 v28, v28, v156
	v_mul_f32_e32 v29, v29, v157
	v_mul_f32_e32 v30, v30, v158
	v_mul_f32_e32 v31, v31, v159
	v_lshlrev_b32_e32 v156, 16, v84
	v_and_b32_e32 v157, 0xffff0000, v84
	v_lshlrev_b32_e32 v158, 16, v85
	v_and_b32_e32 v159, 0xffff0000, v85
	v_mul_f32_e32 v28, v28, v156
	v_mul_f32_e32 v29, v29, v157
	v_mul_f32_e32 v30, v30, v158
	v_mul_f32_e32 v31, v31, v159
	v_mul_f32_e32 v156, 0xbfb8aa3b, v156
	v_mul_f32_e32 v157, 0xbfb8aa3b, v157
	v_mul_f32_e32 v158, 0xbfb8aa3b, v158
	v_mul_f32_e32 v159, 0xbfb8aa3b, v159
	v_exp_f32_e32 v156, v156
	v_exp_f32_e32 v157, v157
	v_exp_f32_e32 v158, v158
	v_exp_f32_e32 v159, v159
	v_add_f32_e32 v156, 1.0, v156
	v_add_f32_e32 v157, 1.0, v157
	v_add_f32_e32 v158, 1.0, v158
	v_add_f32_e32 v159, 1.0, v159
	v_rcp_f32_e32 v156, v156
	v_rcp_f32_e32 v157, v157
	v_rcp_f32_e32 v158, v158
	v_rcp_f32_e32 v159, v159
	v_mul_f32_e32 v28, v156, v28
	v_mul_f32_e32 v29, v157, v29
	v_mul_f32_e32 v30, v158, v30
	v_mul_f32_e32 v31, v159, v31
	v_cvt_pk_bf16_f32 v246, v28, v29
	v_cvt_pk_bf16_f32 v247, v30, v31
	v_add_f32_e32 v24, v24, v170
	v_add_f32_e32 v25, v25, v171
	v_add_f32_e32 v26, v26, v172
	v_add_f32_e32 v27, v27, v173
	v_mul_f32_e32 v24, 0xbfb8aa3b, v24
	v_mul_f32_e32 v25, 0xbfb8aa3b, v25
	v_mul_f32_e32 v26, 0xbfb8aa3b, v26
	v_mul_f32_e32 v27, 0xbfb8aa3b, v27
	v_exp_f32_e32 v24, v24
	v_exp_f32_e32 v25, v25
	v_exp_f32_e32 v26, v26
	v_exp_f32_e32 v27, v27
	v_add_f32_e32 v24, 1.0, v24
	v_add_f32_e32 v25, 1.0, v25
	v_add_f32_e32 v26, 1.0, v26
	v_add_f32_e32 v27, 1.0, v27
	v_rcp_f32_e32 v24, v24
	v_rcp_f32_e32 v25, v25
	v_rcp_f32_e32 v26, v26
	v_rcp_f32_e32 v27, v27
	v_lshlrev_b32_e32 v156, 16, v94
	v_and_b32_e32 v157, 0xffff0000, v94
	v_lshlrev_b32_e32 v158, 16, v95
	v_and_b32_e32 v159, 0xffff0000, v95
	v_mul_f32_e32 v24, v24, v156
	v_mul_f32_e32 v25, v25, v157
	v_mul_f32_e32 v26, v26, v158
	v_mul_f32_e32 v27, v27, v159
	v_lshlrev_b32_e32 v156, 16, v86
	v_and_b32_e32 v157, 0xffff0000, v86
	v_lshlrev_b32_e32 v158, 16, v87
	v_and_b32_e32 v159, 0xffff0000, v87
	v_mul_f32_e32 v24, v24, v156
	v_mul_f32_e32 v25, v25, v157
	v_mul_f32_e32 v26, v26, v158
	v_mul_f32_e32 v27, v27, v159
	v_mul_f32_e32 v156, 0xbfb8aa3b, v156
	v_mul_f32_e32 v157, 0xbfb8aa3b, v157
	v_mul_f32_e32 v158, 0xbfb8aa3b, v158
	v_mul_f32_e32 v159, 0xbfb8aa3b, v159
	v_exp_f32_e32 v156, v156
	v_exp_f32_e32 v157, v157
	v_exp_f32_e32 v158, v158
	v_exp_f32_e32 v159, v159
	v_add_f32_e32 v156, 1.0, v156
	v_add_f32_e32 v157, 1.0, v157
	v_add_f32_e32 v158, 1.0, v158
	v_add_f32_e32 v159, 1.0, v159
	v_rcp_f32_e32 v156, v156
	v_rcp_f32_e32 v157, v157
	v_rcp_f32_e32 v158, v158
	v_rcp_f32_e32 v159, v159
	v_mul_f32_e32 v24, v156, v24
	v_mul_f32_e32 v25, v157, v25
	v_mul_f32_e32 v26, v158, v26
	v_mul_f32_e32 v27, v159, v27
	v_cvt_pk_bf16_f32 v248, v24, v25
	v_cvt_pk_bf16_f32 v249, v26, v27
	s_mov_b32 s38, 0xa0000
	s_mov_b32 s39, 0
	v_lshl_add_u64 v[128:129], v[134:135], 0, s[38:39]
	global_store_dwordx4 v[128:129], v[246:249], off
	v_add_f32_e32 v20, v20, v174
	v_add_f32_e32 v21, v21, v175
	v_add_f32_e32 v22, v22, v176
	v_add_f32_e32 v23, v23, v177
	v_mul_f32_e32 v20, 0xbfb8aa3b, v20
	v_mul_f32_e32 v21, 0xbfb8aa3b, v21
	v_mul_f32_e32 v22, 0xbfb8aa3b, v22
	v_mul_f32_e32 v23, 0xbfb8aa3b, v23
	v_exp_f32_e32 v20, v20
	v_exp_f32_e32 v21, v21
	v_exp_f32_e32 v22, v22
	v_exp_f32_e32 v23, v23
	v_add_f32_e32 v20, 1.0, v20
	v_add_f32_e32 v21, 1.0, v21
	v_add_f32_e32 v22, 1.0, v22
	v_add_f32_e32 v23, 1.0, v23
	v_rcp_f32_e32 v20, v20
	v_rcp_f32_e32 v21, v21
	v_rcp_f32_e32 v22, v22
	v_rcp_f32_e32 v23, v23
	v_lshlrev_b32_e32 v156, 16, v88
	v_and_b32_e32 v157, 0xffff0000, v88
	v_lshlrev_b32_e32 v158, 16, v89
	v_and_b32_e32 v159, 0xffff0000, v89
	v_mul_f32_e32 v20, v20, v156
	v_mul_f32_e32 v21, v21, v157
	v_mul_f32_e32 v22, v22, v158
	v_mul_f32_e32 v23, v23, v159
	v_lshlrev_b32_e32 v156, 16, v80
	v_and_b32_e32 v157, 0xffff0000, v80
	v_lshlrev_b32_e32 v158, 16, v81
	v_and_b32_e32 v159, 0xffff0000, v81
	v_mul_f32_e32 v20, v20, v156
	v_mul_f32_e32 v21, v21, v157
	v_mul_f32_e32 v22, v22, v158
	v_mul_f32_e32 v23, v23, v159
	v_mul_f32_e32 v156, 0xbfb8aa3b, v156
	v_mul_f32_e32 v157, 0xbfb8aa3b, v157
	v_mul_f32_e32 v158, 0xbfb8aa3b, v158
	v_mul_f32_e32 v159, 0xbfb8aa3b, v159
	v_exp_f32_e32 v156, v156
	v_exp_f32_e32 v157, v157
	v_exp_f32_e32 v158, v158
	v_exp_f32_e32 v159, v159
	v_add_f32_e32 v156, 1.0, v156
	v_add_f32_e32 v157, 1.0, v157
	v_add_f32_e32 v158, 1.0, v158
	v_add_f32_e32 v159, 1.0, v159
	v_rcp_f32_e32 v156, v156
	v_rcp_f32_e32 v157, v157
	v_rcp_f32_e32 v158, v158
	v_rcp_f32_e32 v159, v159
	v_mul_f32_e32 v20, v156, v20
	v_mul_f32_e32 v21, v157, v21
	v_mul_f32_e32 v22, v158, v22
	v_mul_f32_e32 v23, v159, v23
	v_cvt_pk_bf16_f32 v250, v20, v21
	v_cvt_pk_bf16_f32 v251, v22, v23
	v_add_f32_e32 v16, v16, v178
	v_add_f32_e32 v17, v17, v179
	v_add_f32_e32 v18, v18, v180
	v_add_f32_e32 v19, v19, v181
	v_mul_f32_e32 v16, 0xbfb8aa3b, v16
	v_mul_f32_e32 v17, 0xbfb8aa3b, v17
	v_mul_f32_e32 v18, 0xbfb8aa3b, v18
	v_mul_f32_e32 v19, 0xbfb8aa3b, v19
	v_exp_f32_e32 v16, v16
	v_exp_f32_e32 v17, v17
	v_exp_f32_e32 v18, v18
	v_exp_f32_e32 v19, v19
	v_add_f32_e32 v16, 1.0, v16
	v_add_f32_e32 v17, 1.0, v17
	v_add_f32_e32 v18, 1.0, v18
	v_add_f32_e32 v19, 1.0, v19
	v_rcp_f32_e32 v16, v16
	v_rcp_f32_e32 v17, v17
	v_rcp_f32_e32 v18, v18
	v_rcp_f32_e32 v19, v19
	v_lshlrev_b32_e32 v156, 16, v90
	v_and_b32_e32 v157, 0xffff0000, v90
	v_lshlrev_b32_e32 v158, 16, v91
	v_and_b32_e32 v159, 0xffff0000, v91
	v_mul_f32_e32 v16, v16, v156
	v_mul_f32_e32 v17, v17, v157
	v_mul_f32_e32 v18, v18, v158
	v_mul_f32_e32 v19, v19, v159
	v_lshlrev_b32_e32 v156, 16, v82
	v_and_b32_e32 v157, 0xffff0000, v82
	v_lshlrev_b32_e32 v158, 16, v83
	v_and_b32_e32 v159, 0xffff0000, v83
	v_mul_f32_e32 v16, v16, v156
	v_mul_f32_e32 v17, v17, v157
	v_mul_f32_e32 v18, v18, v158
	v_mul_f32_e32 v19, v19, v159
	v_mul_f32_e32 v156, 0xbfb8aa3b, v156
	v_mul_f32_e32 v157, 0xbfb8aa3b, v157
	v_mul_f32_e32 v158, 0xbfb8aa3b, v158
	v_mul_f32_e32 v159, 0xbfb8aa3b, v159
	v_exp_f32_e32 v156, v156
	v_exp_f32_e32 v157, v157
	v_exp_f32_e32 v158, v158
	v_exp_f32_e32 v159, v159
	v_add_f32_e32 v156, 1.0, v156
	v_add_f32_e32 v157, 1.0, v157
	v_add_f32_e32 v158, 1.0, v158
	v_add_f32_e32 v159, 1.0, v159
	v_rcp_f32_e32 v156, v156
	v_rcp_f32_e32 v157, v157
	v_rcp_f32_e32 v158, v158
	v_rcp_f32_e32 v159, v159
	v_mul_f32_e32 v16, v156, v16
	v_mul_f32_e32 v17, v157, v17
	v_mul_f32_e32 v18, v158, v18
	v_mul_f32_e32 v19, v159, v19
	v_cvt_pk_bf16_f32 v252, v16, v17
	v_cvt_pk_bf16_f32 v253, v18, v19
	global_store_dwordx4 v[128:129], v[250:253], off offset:256
	s_waitcnt vmcnt(6)
	v_add_f32_e32 v12, v12, v166
	v_add_f32_e32 v13, v13, v167
	v_add_f32_e32 v14, v14, v168
	v_add_f32_e32 v15, v15, v169
	v_mul_f32_e32 v12, 0xbfb8aa3b, v12
	v_mul_f32_e32 v13, 0xbfb8aa3b, v13
	v_mul_f32_e32 v14, 0xbfb8aa3b, v14
	v_mul_f32_e32 v15, 0xbfb8aa3b, v15
	v_exp_f32_e32 v12, v12
	v_exp_f32_e32 v13, v13
	v_exp_f32_e32 v14, v14
	v_exp_f32_e32 v15, v15
	v_add_f32_e32 v12, 1.0, v12
	v_add_f32_e32 v13, 1.0, v13
	v_add_f32_e32 v14, 1.0, v14
	v_add_f32_e32 v15, 1.0, v15
	v_rcp_f32_e32 v12, v12
	v_rcp_f32_e32 v13, v13
	v_rcp_f32_e32 v14, v14
	v_rcp_f32_e32 v15, v15
	v_lshlrev_b32_e32 v156, 16, v76
	v_and_b32_e32 v157, 0xffff0000, v76
	v_lshlrev_b32_e32 v158, 16, v77
	v_and_b32_e32 v159, 0xffff0000, v77
	v_mul_f32_e32 v12, v12, v156
	v_mul_f32_e32 v13, v13, v157
	v_mul_f32_e32 v14, v14, v158
	v_mul_f32_e32 v15, v15, v159
	v_lshlrev_b32_e32 v156, 16, v68
	v_and_b32_e32 v157, 0xffff0000, v68
	v_lshlrev_b32_e32 v158, 16, v69
	v_and_b32_e32 v159, 0xffff0000, v69
	v_mul_f32_e32 v12, v12, v156
	v_mul_f32_e32 v13, v13, v157
	v_mul_f32_e32 v14, v14, v158
	v_mul_f32_e32 v15, v15, v159
	v_mul_f32_e32 v156, 0xbfb8aa3b, v156
	v_mul_f32_e32 v157, 0xbfb8aa3b, v157
	v_mul_f32_e32 v158, 0xbfb8aa3b, v158
	v_mul_f32_e32 v159, 0xbfb8aa3b, v159
	v_exp_f32_e32 v156, v156
	v_exp_f32_e32 v157, v157
	v_exp_f32_e32 v158, v158
	v_exp_f32_e32 v159, v159
	v_add_f32_e32 v156, 1.0, v156
	v_add_f32_e32 v157, 1.0, v157
	v_add_f32_e32 v158, 1.0, v158
	v_add_f32_e32 v159, 1.0, v159
	v_rcp_f32_e32 v156, v156
	v_rcp_f32_e32 v157, v157
	v_rcp_f32_e32 v158, v158
	v_rcp_f32_e32 v159, v159
	v_mul_f32_e32 v12, v156, v12
	v_mul_f32_e32 v13, v157, v13
	v_mul_f32_e32 v14, v158, v14
	v_mul_f32_e32 v15, v159, v15
	v_cvt_pk_bf16_f32 v246, v12, v13
	v_cvt_pk_bf16_f32 v247, v14, v15
	v_add_f32_e32 v8, v8, v170
	v_add_f32_e32 v9, v9, v171
	v_add_f32_e32 v10, v10, v172
	v_add_f32_e32 v11, v11, v173
	v_mul_f32_e32 v8, 0xbfb8aa3b, v8
	v_mul_f32_e32 v9, 0xbfb8aa3b, v9
	v_mul_f32_e32 v10, 0xbfb8aa3b, v10
	v_mul_f32_e32 v11, 0xbfb8aa3b, v11
	v_exp_f32_e32 v8, v8
	v_exp_f32_e32 v9, v9
	v_exp_f32_e32 v10, v10
	v_exp_f32_e32 v11, v11
	v_add_f32_e32 v8, 1.0, v8
	v_add_f32_e32 v9, 1.0, v9
	v_add_f32_e32 v10, 1.0, v10
	v_add_f32_e32 v11, 1.0, v11
	v_rcp_f32_e32 v8, v8
	v_rcp_f32_e32 v9, v9
	v_rcp_f32_e32 v10, v10
	v_rcp_f32_e32 v11, v11
	v_lshlrev_b32_e32 v156, 16, v78
	v_and_b32_e32 v157, 0xffff0000, v78
	v_lshlrev_b32_e32 v158, 16, v79
	v_and_b32_e32 v159, 0xffff0000, v79
	v_mul_f32_e32 v8, v8, v156
	v_mul_f32_e32 v9, v9, v157
	v_mul_f32_e32 v10, v10, v158
	v_mul_f32_e32 v11, v11, v159
	v_lshlrev_b32_e32 v156, 16, v70
	v_and_b32_e32 v157, 0xffff0000, v70
	v_lshlrev_b32_e32 v158, 16, v71
	v_and_b32_e32 v159, 0xffff0000, v71
	v_mul_f32_e32 v8, v8, v156
	v_mul_f32_e32 v9, v9, v157
	v_mul_f32_e32 v10, v10, v158
	v_mul_f32_e32 v11, v11, v159
	v_mul_f32_e32 v156, 0xbfb8aa3b, v156
	v_mul_f32_e32 v157, 0xbfb8aa3b, v157
	v_mul_f32_e32 v158, 0xbfb8aa3b, v158
	v_mul_f32_e32 v159, 0xbfb8aa3b, v159
	v_exp_f32_e32 v156, v156
	v_exp_f32_e32 v157, v157
	v_exp_f32_e32 v158, v158
	v_exp_f32_e32 v159, v159
	v_add_f32_e32 v156, 1.0, v156
	v_add_f32_e32 v157, 1.0, v157
	v_add_f32_e32 v158, 1.0, v158
	v_add_f32_e32 v159, 1.0, v159
	v_rcp_f32_e32 v156, v156
	v_rcp_f32_e32 v157, v157
	v_rcp_f32_e32 v158, v158
	v_rcp_f32_e32 v159, v159
	v_mul_f32_e32 v8, v156, v8
	v_mul_f32_e32 v9, v157, v9
	v_mul_f32_e32 v10, v158, v10
	v_mul_f32_e32 v11, v159, v11
	v_cvt_pk_bf16_f32 v248, v8, v9
	v_cvt_pk_bf16_f32 v249, v10, v11
	s_mov_b32 s38, 0xb0000
	s_mov_b32 s39, 0
	v_lshl_add_u64 v[128:129], v[134:135], 0, s[38:39]
	global_store_dwordx4 v[128:129], v[246:249], off
	v_add_f32_e32 v4, v4, v174
	v_add_f32_e32 v5, v5, v175
	v_add_f32_e32 v6, v6, v176
	v_add_f32_e32 v7, v7, v177
	v_mul_f32_e32 v4, 0xbfb8aa3b, v4
	v_mul_f32_e32 v5, 0xbfb8aa3b, v5
	v_mul_f32_e32 v6, 0xbfb8aa3b, v6
	v_mul_f32_e32 v7, 0xbfb8aa3b, v7
	v_exp_f32_e32 v4, v4
	v_exp_f32_e32 v5, v5
	v_exp_f32_e32 v6, v6
	v_exp_f32_e32 v7, v7
	v_add_f32_e32 v4, 1.0, v4
	v_add_f32_e32 v5, 1.0, v5
	v_add_f32_e32 v6, 1.0, v6
	v_add_f32_e32 v7, 1.0, v7
	v_rcp_f32_e32 v4, v4
	v_rcp_f32_e32 v5, v5
	v_rcp_f32_e32 v6, v6
	v_rcp_f32_e32 v7, v7
	v_lshlrev_b32_e32 v156, 16, v72
	v_and_b32_e32 v157, 0xffff0000, v72
	v_lshlrev_b32_e32 v158, 16, v73
	v_and_b32_e32 v159, 0xffff0000, v73
	v_mul_f32_e32 v4, v4, v156
	v_mul_f32_e32 v5, v5, v157
	v_mul_f32_e32 v6, v6, v158
	v_mul_f32_e32 v7, v7, v159
	v_lshlrev_b32_e32 v156, 16, v64
	v_and_b32_e32 v157, 0xffff0000, v64
	v_lshlrev_b32_e32 v158, 16, v65
	v_and_b32_e32 v159, 0xffff0000, v65
	v_mul_f32_e32 v4, v4, v156
	v_mul_f32_e32 v5, v5, v157
	v_mul_f32_e32 v6, v6, v158
	v_mul_f32_e32 v7, v7, v159
	v_mul_f32_e32 v156, 0xbfb8aa3b, v156
	v_mul_f32_e32 v157, 0xbfb8aa3b, v157
	v_mul_f32_e32 v158, 0xbfb8aa3b, v158
	v_mul_f32_e32 v159, 0xbfb8aa3b, v159
	v_exp_f32_e32 v156, v156
	v_exp_f32_e32 v157, v157
	v_exp_f32_e32 v158, v158
	v_exp_f32_e32 v159, v159
	v_add_f32_e32 v156, 1.0, v156
	v_add_f32_e32 v157, 1.0, v157
	v_add_f32_e32 v158, 1.0, v158
	v_add_f32_e32 v159, 1.0, v159
	v_rcp_f32_e32 v156, v156
	v_rcp_f32_e32 v157, v157
	v_rcp_f32_e32 v158, v158
	v_rcp_f32_e32 v159, v159
	v_mul_f32_e32 v4, v156, v4
	v_mul_f32_e32 v5, v157, v5
	v_mul_f32_e32 v6, v158, v6
	v_mul_f32_e32 v7, v159, v7
	v_cvt_pk_bf16_f32 v250, v4, v5
	v_cvt_pk_bf16_f32 v251, v6, v7
	v_add_f32_e32 v0, v0, v178
	v_add_f32_e32 v1, v1, v179
	v_add_f32_e32 v2, v2, v180
	v_add_f32_e32 v3, v3, v181
	v_mul_f32_e32 v0, 0xbfb8aa3b, v0
	v_mul_f32_e32 v1, 0xbfb8aa3b, v1
	v_mul_f32_e32 v2, 0xbfb8aa3b, v2
	v_mul_f32_e32 v3, 0xbfb8aa3b, v3
	v_exp_f32_e32 v0, v0
	v_exp_f32_e32 v1, v1
	v_exp_f32_e32 v2, v2
	v_exp_f32_e32 v3, v3
	v_add_f32_e32 v0, 1.0, v0
	v_add_f32_e32 v1, 1.0, v1
	v_add_f32_e32 v2, 1.0, v2
	v_add_f32_e32 v3, 1.0, v3
	v_rcp_f32_e32 v0, v0
	v_rcp_f32_e32 v1, v1
	v_rcp_f32_e32 v2, v2
	v_rcp_f32_e32 v3, v3
	v_lshlrev_b32_e32 v156, 16, v74
	v_and_b32_e32 v157, 0xffff0000, v74
	v_lshlrev_b32_e32 v158, 16, v75
	v_and_b32_e32 v159, 0xffff0000, v75
	v_mul_f32_e32 v0, v0, v156
	v_mul_f32_e32 v1, v1, v157
	v_mul_f32_e32 v2, v2, v158
	v_mul_f32_e32 v3, v3, v159
	v_lshlrev_b32_e32 v156, 16, v66
	v_and_b32_e32 v157, 0xffff0000, v66
	v_lshlrev_b32_e32 v158, 16, v67
	v_and_b32_e32 v159, 0xffff0000, v67
	v_mul_f32_e32 v0, v0, v156
	v_mul_f32_e32 v1, v1, v157
	v_mul_f32_e32 v2, v2, v158
	v_mul_f32_e32 v3, v3, v159
	v_mul_f32_e32 v156, 0xbfb8aa3b, v156
	v_mul_f32_e32 v157, 0xbfb8aa3b, v157
	v_mul_f32_e32 v158, 0xbfb8aa3b, v158
	v_mul_f32_e32 v159, 0xbfb8aa3b, v159
	v_exp_f32_e32 v156, v156
	v_exp_f32_e32 v157, v157
	v_exp_f32_e32 v158, v158
	v_exp_f32_e32 v159, v159
	v_add_f32_e32 v156, 1.0, v156
	v_add_f32_e32 v157, 1.0, v157
	v_add_f32_e32 v158, 1.0, v158
	v_add_f32_e32 v159, 1.0, v159
	v_rcp_f32_e32 v156, v156
	v_rcp_f32_e32 v157, v157
	v_rcp_f32_e32 v158, v158
	v_rcp_f32_e32 v159, v159
	v_mul_f32_e32 v0, v156, v0
	v_mul_f32_e32 v1, v157, v1
	v_mul_f32_e32 v2, v158, v2
	v_mul_f32_e32 v3, v159, v3
	v_cvt_pk_bf16_f32 v252, v0, v1
	v_cvt_pk_bf16_f32 v253, v2, v3
	global_store_dwordx4 v[128:129], v[250:253], off offset:256
	s_cbranch_vccnz .LBB0_370
	s_andn2_b64 vcc, exec, s[10:11]
	s_cbranch_vccnz .LBB0_369
	s_barrier
	s_branch .LBB0_369
